# FFN-down epilogue: residual 8-byte loads widened to 16-byte (inverse permlane16 swap), waits re-derived, final-LN placement kept
# speedup vs baseline: 1.0047x; 1.0047x over previous
.Lffn_nz:
	s_waitcnt vmcnt(0)
	ds_bpermute_b32 v200, v252, v158
	ds_bpermute_b32 v201, v252, v159
	ds_bpermute_b32 v202, v252, v154
	ds_bpermute_b32 v203, v252, v155
	s_waitcnt lgkmcnt(0)
	ds_bpermute_b32 v204, v252, v62
	ds_bpermute_b32 v205, v252, v63
	ds_bpermute_b32 v206, v252, v58
	ds_bpermute_b32 v207, v252, v59
	v_pk_fma_f32 v[230:231], v[156:157], v[112:113], v[116:117] op_sel_hi:[1,0,0]
	v_pk_fma_f32 v[232:233], v[158:159], v[112:113], v[116:117] op_sel_hi:[1,0,0]
	v_fmac_f32_e32 v230, v201, v113
	v_fmac_f32_e32 v231, v156, v113
	v_fmac_f32_e32 v232, v157, v113
	v_fmac_f32_e32 v233, v158, v113
	v_pk_fma_f32 v[230:231], v[200:201], v[114:115], v[230:231] op_sel_hi:[1,0,1]
	v_pk_fma_f32 v[232:233], v[156:157], v[114:115], v[232:233] op_sel_hi:[1,0,1]
	v_pk_fma_f32 v[234:235], v[152:153], v[118:119], v[122:123] op_sel_hi:[1,0,0]
	v_pk_fma_f32 v[236:237], v[154:155], v[118:119], v[122:123] op_sel_hi:[1,0,0]
	v_fmac_f32_e32 v234, v203, v119
	v_fmac_f32_e32 v235, v152, v119
	v_fmac_f32_e32 v236, v153, v119
	v_fmac_f32_e32 v237, v154, v119
	v_pk_fma_f32 v[234:235], v[202:203], v[120:121], v[234:235] op_sel_hi:[1,0,1]
	v_pk_fma_f32 v[236:237], v[152:153], v[120:121], v[236:237] op_sel_hi:[1,0,1]
	v_pk_mul_f32 v[238:239], v[230:231], v[230:231]
	v_pk_mul_f32 v[240:241], v[232:233], v[232:233]
	v_pk_fma_f32 v[238:239], v[238:239], v[248:249], v[246:247]
	v_pk_fma_f32 v[240:241], v[240:241], v[248:249], v[246:247]
	v_pk_mul_f32 v[238:239], v[230:231], v[238:239]
	v_pk_mul_f32 v[240:241], v[232:233], v[240:241]
	v_exp_f32_e32 v238, v238
	v_exp_f32_e32 v239, v239
	v_exp_f32_e32 v240, v240
	v_exp_f32_e32 v241, v241
	v_pk_add_f32 v[238:239], v[238:239], 1.0 op_sel_hi:[1,0]
	v_pk_add_f32 v[240:241], v[240:241], 1.0 op_sel_hi:[1,0]
	v_rcp_f32_e32 v238, v238
	v_rcp_f32_e32 v239, v239
	v_rcp_f32_e32 v240, v240
	v_rcp_f32_e32 v241, v241
	v_pk_mul_f32 v[230:231], v[230:231], v[234:235]
	v_pk_mul_f32 v[232:233], v[232:233], v[236:237]
	v_pk_mul_f32 v[238:239], v[230:231], v[238:239]
	v_pk_mul_f32 v[240:241], v[232:233], v[240:241]
	v_cvt_pk_bf16_f32 v212, v238, v239
	v_cvt_pk_bf16_f32 v213, v240, v241
	s_mov_b64 vcc, s[30:31]
	s_nop 0
	v_mov_b32_dpp v214, v212 quad_perm:[1,0,3,2] row_mask:0xf bank_mask:0xf
	v_mov_b32_dpp v215, v213 quad_perm:[1,0,3,2] row_mask:0xf bank_mask:0xf
	v_perm_b32 v216, v214, v212, v253
	v_perm_b32 v217, v215, v213, v253
	s_nop 1
	v_mov_b32_dpp v218, v216 quad_perm:[2,3,0,1] row_mask:0xf bank_mask:0xf
	v_mov_b32_dpp v219, v217 quad_perm:[2,3,0,1] row_mask:0xf bank_mask:0xf
	v_cndmask_b32_e32 v176, v216, v219, vcc
	v_cndmask_b32_e32 v177, v218, v217, vcc
	s_waitcnt lgkmcnt(0)
	s_mov_b64 vcc, s[28:29]
	v_cndmask_b32_e32 v208, v150, v158, vcc
	v_cndmask_b32_e32 v209, v151, v159, vcc
	v_cndmask_b32_e32 v210, v146, v154, vcc
	v_cndmask_b32_e32 v211, v147, v155, vcc
	ds_bpermute_b32 v200, v252, v208
	ds_bpermute_b32 v201, v252, v209
	ds_bpermute_b32 v202, v252, v210
	ds_bpermute_b32 v203, v252, v211
	v_pk_fma_f32 v[230:231], v[60:61], v[124:125], v[128:129] op_sel_hi:[1,0,0]
	v_pk_fma_f32 v[232:233], v[62:63], v[124:125], v[128:129] op_sel_hi:[1,0,0]
	v_fmac_f32_e32 v230, v205, v125
	v_fmac_f32_e32 v231, v60, v125
	v_fmac_f32_e32 v232, v61, v125
	v_fmac_f32_e32 v233, v62, v125
	v_pk_fma_f32 v[230:231], v[204:205], v[126:127], v[230:231] op_sel_hi:[1,0,1]
	v_pk_fma_f32 v[232:233], v[60:61], v[126:127], v[232:233] op_sel_hi:[1,0,1]
	v_pk_fma_f32 v[234:235], v[56:57], v[130:131], v[134:135] op_sel_hi:[1,0,0]
	v_pk_fma_f32 v[236:237], v[58:59], v[130:131], v[134:135] op_sel_hi:[1,0,0]
	v_fmac_f32_e32 v234, v207, v131
	v_fmac_f32_e32 v235, v56, v131
	v_fmac_f32_e32 v236, v57, v131
	v_fmac_f32_e32 v237, v58, v131
	v_pk_fma_f32 v[234:235], v[206:207], v[132:133], v[234:235] op_sel_hi:[1,0,1]
	v_pk_fma_f32 v[236:237], v[56:57], v[132:133], v[236:237] op_sel_hi:[1,0,1]
	v_pk_mul_f32 v[238:239], v[230:231], v[230:231]
	v_pk_mul_f32 v[240:241], v[232:233], v[232:233]
	v_pk_fma_f32 v[238:239], v[238:239], v[248:249], v[246:247]
	v_pk_fma_f32 v[240:241], v[240:241], v[248:249], v[246:247]
	v_pk_mul_f32 v[238:239], v[230:231], v[238:239]
	v_pk_mul_f32 v[240:241], v[232:233], v[240:241]
	v_exp_f32_e32 v238, v238
	v_exp_f32_e32 v239, v239
	v_exp_f32_e32 v240, v240
	v_exp_f32_e32 v241, v241
	v_pk_add_f32 v[238:239], v[238:239], 1.0 op_sel_hi:[1,0]
	v_pk_add_f32 v[240:241], v[240:241], 1.0 op_sel_hi:[1,0]
	v_rcp_f32_e32 v238, v238
	v_rcp_f32_e32 v239, v239
	v_rcp_f32_e32 v240, v240
	v_rcp_f32_e32 v241, v241
	v_pk_mul_f32 v[230:231], v[230:231], v[234:235]
	v_pk_mul_f32 v[232:233], v[232:233], v[236:237]
	v_pk_mul_f32 v[238:239], v[230:231], v[238:239]
	v_pk_mul_f32 v[240:241], v[232:233], v[240:241]
	v_cvt_pk_bf16_f32 v212, v238, v239
	v_cvt_pk_bf16_f32 v213, v240, v241
	s_mov_b64 vcc, s[30:31]
	s_nop 0
	v_mov_b32_dpp v214, v212 quad_perm:[1,0,3,2] row_mask:0xf bank_mask:0xf
	v_mov_b32_dpp v215, v213 quad_perm:[1,0,3,2] row_mask:0xf bank_mask:0xf
	v_perm_b32 v216, v214, v212, v253
	v_perm_b32 v217, v215, v213, v253
	s_nop 1
	v_mov_b32_dpp v218, v216 quad_perm:[2,3,0,1] row_mask:0xf bank_mask:0xf
	v_mov_b32_dpp v219, v217 quad_perm:[2,3,0,1] row_mask:0xf bank_mask:0xf
	v_cndmask_b32_e32 v178, v216, v219, vcc
	v_cndmask_b32_e32 v179, v218, v217, vcc
	s_movk_i32 s15, 0x1002
	v_cmp_gt_i32_e64 s[24:25], s15, v251
	s_sub_u32 s84, s58, 0x2c00
	s_subb_u32 s85, s59, 0
	s_and_b64 s[24:25], s[24:25], s[36:37]
	s_mov_b64 exec, s[24:25]
	global_store_dwordx4 v250, v[176:179], s[84:85] nt
	s_mov_b64 exec, -1
	s_nop 0
	s_waitcnt lgkmcnt(0)
	s_mov_b64 vcc, s[28:29]
	v_cndmask_b32_e32 v208, v54, v62, vcc
	v_cndmask_b32_e32 v209, v55, v63, vcc
	v_cndmask_b32_e32 v210, v50, v58, vcc
	v_cndmask_b32_e32 v211, v51, v59, vcc
	ds_bpermute_b32 v204, v252, v208
	ds_bpermute_b32 v205, v252, v209
	ds_bpermute_b32 v206, v252, v210
	ds_bpermute_b32 v207, v252, v211
	v_pk_fma_f32 v[230:231], v[148:149], v[112:113], v[116:117] op_sel_hi:[1,0,0]
	v_pk_fma_f32 v[232:233], v[150:151], v[112:113], v[116:117] op_sel_hi:[1,0,0]
	v_fmac_f32_e32 v230, v201, v113
	v_fmac_f32_e32 v231, v148, v113
	v_fmac_f32_e32 v232, v149, v113
	v_fmac_f32_e32 v233, v150, v113
	v_pk_fma_f32 v[230:231], v[200:201], v[114:115], v[230:231] op_sel_hi:[1,0,1]
	v_pk_fma_f32 v[232:233], v[148:149], v[114:115], v[232:233] op_sel_hi:[1,0,1]
	v_pk_fma_f32 v[234:235], v[144:145], v[118:119], v[122:123] op_sel_hi:[1,0,0]
	v_pk_fma_f32 v[236:237], v[146:147], v[118:119], v[122:123] op_sel_hi:[1,0,0]
	v_fmac_f32_e32 v234, v203, v119
	v_fmac_f32_e32 v235, v144, v119
	v_fmac_f32_e32 v236, v145, v119
	v_fmac_f32_e32 v237, v146, v119
	v_pk_fma_f32 v[234:235], v[202:203], v[120:121], v[234:235] op_sel_hi:[1,0,1]
	v_pk_fma_f32 v[236:237], v[144:145], v[120:121], v[236:237] op_sel_hi:[1,0,1]
	v_pk_mul_f32 v[238:239], v[230:231], v[230:231]
	v_pk_mul_f32 v[240:241], v[232:233], v[232:233]
	v_pk_fma_f32 v[238:239], v[238:239], v[248:249], v[246:247]
	v_pk_fma_f32 v[240:241], v[240:241], v[248:249], v[246:247]
	v_pk_mul_f32 v[238:239], v[230:231], v[238:239]
	v_pk_mul_f32 v[240:241], v[232:233], v[240:241]
	v_exp_f32_e32 v238, v238
	v_exp_f32_e32 v239, v239
	v_exp_f32_e32 v240, v240
	v_exp_f32_e32 v241, v241
	v_pk_add_f32 v[238:239], v[238:239], 1.0 op_sel_hi:[1,0]
	v_pk_add_f32 v[240:241], v[240:241], 1.0 op_sel_hi:[1,0]
	v_rcp_f32_e32 v238, v238
	v_rcp_f32_e32 v239, v239
	v_rcp_f32_e32 v240, v240
	v_rcp_f32_e32 v241, v241
	v_pk_mul_f32 v[230:231], v[230:231], v[234:235]
	v_pk_mul_f32 v[232:233], v[232:233], v[236:237]
	v_pk_mul_f32 v[238:239], v[230:231], v[238:239]
	v_pk_mul_f32 v[240:241], v[232:233], v[240:241]
	v_cvt_pk_bf16_f32 v212, v238, v239
	v_cvt_pk_bf16_f32 v213, v240, v241
	s_mov_b64 vcc, s[30:31]
	s_nop 0
	v_mov_b32_dpp v214, v212 quad_perm:[1,0,3,2] row_mask:0xf bank_mask:0xf
	v_mov_b32_dpp v215, v213 quad_perm:[1,0,3,2] row_mask:0xf bank_mask:0xf
	v_perm_b32 v216, v214, v212, v253
	v_perm_b32 v217, v215, v213, v253
	s_nop 1
	v_mov_b32_dpp v218, v216 quad_perm:[2,3,0,1] row_mask:0xf bank_mask:0xf
	v_mov_b32_dpp v219, v217 quad_perm:[2,3,0,1] row_mask:0xf bank_mask:0xf
	v_cndmask_b32_e32 v180, v216, v219, vcc
	v_cndmask_b32_e32 v181, v218, v217, vcc
	s_waitcnt lgkmcnt(0)
	s_mov_b64 vcc, s[28:29]
	v_cndmask_b32_e32 v208, v142, v150, vcc
	v_cndmask_b32_e32 v209, v143, v151, vcc
	v_cndmask_b32_e32 v210, v138, v146, vcc
	v_cndmask_b32_e32 v211, v139, v147, vcc
	ds_bpermute_b32 v200, v252, v208
	ds_bpermute_b32 v201, v252, v209
	ds_bpermute_b32 v202, v252, v210
	ds_bpermute_b32 v203, v252, v211
	v_pk_fma_f32 v[230:231], v[52:53], v[124:125], v[128:129] op_sel_hi:[1,0,0]
	v_pk_fma_f32 v[232:233], v[54:55], v[124:125], v[128:129] op_sel_hi:[1,0,0]
	v_fmac_f32_e32 v230, v205, v125
	v_fmac_f32_e32 v231, v52, v125
	v_fmac_f32_e32 v232, v53, v125
	v_fmac_f32_e32 v233, v54, v125
	v_pk_fma_f32 v[230:231], v[204:205], v[126:127], v[230:231] op_sel_hi:[1,0,1]
	v_pk_fma_f32 v[232:233], v[52:53], v[126:127], v[232:233] op_sel_hi:[1,0,1]
	v_pk_fma_f32 v[234:235], v[48:49], v[130:131], v[134:135] op_sel_hi:[1,0,0]
	v_pk_fma_f32 v[236:237], v[50:51], v[130:131], v[134:135] op_sel_hi:[1,0,0]
	v_fmac_f32_e32 v234, v207, v131
	v_fmac_f32_e32 v235, v48, v131
	v_fmac_f32_e32 v236, v49, v131
	v_fmac_f32_e32 v237, v50, v131
	v_pk_fma_f32 v[234:235], v[206:207], v[132:133], v[234:235] op_sel_hi:[1,0,1]
	v_pk_fma_f32 v[236:237], v[48:49], v[132:133], v[236:237] op_sel_hi:[1,0,1]
	v_pk_mul_f32 v[238:239], v[230:231], v[230:231]
	v_pk_mul_f32 v[240:241], v[232:233], v[232:233]
	v_pk_fma_f32 v[238:239], v[238:239], v[248:249], v[246:247]
	v_pk_fma_f32 v[240:241], v[240:241], v[248:249], v[246:247]
	v_pk_mul_f32 v[238:239], v[230:231], v[238:239]
	v_pk_mul_f32 v[240:241], v[232:233], v[240:241]
	v_exp_f32_e32 v238, v238
	v_exp_f32_e32 v239, v239
	v_exp_f32_e32 v240, v240
	v_exp_f32_e32 v241, v241
	v_pk_add_f32 v[238:239], v[238:239], 1.0 op_sel_hi:[1,0]
	v_pk_add_f32 v[240:241], v[240:241], 1.0 op_sel_hi:[1,0]
	v_rcp_f32_e32 v238, v238
	v_rcp_f32_e32 v239, v239
	v_rcp_f32_e32 v240, v240
	v_rcp_f32_e32 v241, v241
	v_pk_mul_f32 v[230:231], v[230:231], v[234:235]
	v_pk_mul_f32 v[232:233], v[232:233], v[236:237]
	v_pk_mul_f32 v[238:239], v[230:231], v[238:239]
	v_pk_mul_f32 v[240:241], v[232:233], v[240:241]
	v_cvt_pk_bf16_f32 v212, v238, v239
	v_cvt_pk_bf16_f32 v213, v240, v241
	s_mov_b64 vcc, s[30:31]
	s_nop 0
	v_mov_b32_dpp v214, v212 quad_perm:[1,0,3,2] row_mask:0xf bank_mask:0xf
	v_mov_b32_dpp v215, v213 quad_perm:[1,0,3,2] row_mask:0xf bank_mask:0xf
	v_perm_b32 v216, v214, v212, v253
	v_perm_b32 v217, v215, v213, v253
	s_nop 1
	v_mov_b32_dpp v218, v216 quad_perm:[2,3,0,1] row_mask:0xf bank_mask:0xf
	v_mov_b32_dpp v219, v217 quad_perm:[2,3,0,1] row_mask:0xf bank_mask:0xf
	v_cndmask_b32_e32 v182, v216, v219, vcc
	v_cndmask_b32_e32 v183, v218, v217, vcc
	s_movk_i32 s15, 0xff2
	v_cmp_gt_i32_e64 s[24:25], s15, v251
	s_add_u32 s84, s58, 0x13400
	s_addc_u32 s85, s59, 0
	s_mov_b64 exec, s[24:25]
	global_store_dwordx4 v250, v[180:183], s[84:85] nt
	s_mov_b64 exec, -1
	s_nop 0
	s_waitcnt lgkmcnt(0)
	s_mov_b64 vcc, s[28:29]
	v_cndmask_b32_e32 v208, v46, v54, vcc
	v_cndmask_b32_e32 v209, v47, v55, vcc
	v_cndmask_b32_e32 v210, v42, v50, vcc
	v_cndmask_b32_e32 v211, v43, v51, vcc
	ds_bpermute_b32 v204, v252, v208
	ds_bpermute_b32 v205, v252, v209
	ds_bpermute_b32 v206, v252, v210
	ds_bpermute_b32 v207, v252, v211
	v_pk_fma_f32 v[230:231], v[140:141], v[112:113], v[116:117] op_sel_hi:[1,0,0]
	v_pk_fma_f32 v[232:233], v[142:143], v[112:113], v[116:117] op_sel_hi:[1,0,0]
	v_fmac_f32_e32 v230, v201, v113
	v_fmac_f32_e32 v231, v140, v113
	v_fmac_f32_e32 v232, v141, v113
	v_fmac_f32_e32 v233, v142, v113
	v_pk_fma_f32 v[230:231], v[200:201], v[114:115], v[230:231] op_sel_hi:[1,0,1]
	v_pk_fma_f32 v[232:233], v[140:141], v[114:115], v[232:233] op_sel_hi:[1,0,1]
	v_pk_fma_f32 v[234:235], v[136:137], v[118:119], v[122:123] op_sel_hi:[1,0,0]
	v_pk_fma_f32 v[236:237], v[138:139], v[118:119], v[122:123] op_sel_hi:[1,0,0]
	v_fmac_f32_e32 v234, v203, v119
	v_fmac_f32_e32 v235, v136, v119
	v_fmac_f32_e32 v236, v137, v119
	v_fmac_f32_e32 v237, v138, v119
	v_pk_fma_f32 v[234:235], v[202:203], v[120:121], v[234:235] op_sel_hi:[1,0,1]
	v_pk_fma_f32 v[236:237], v[136:137], v[120:121], v[236:237] op_sel_hi:[1,0,1]
	v_pk_mul_f32 v[238:239], v[230:231], v[230:231]
	v_pk_mul_f32 v[240:241], v[232:233], v[232:233]
	v_pk_fma_f32 v[238:239], v[238:239], v[248:249], v[246:247]
	v_pk_fma_f32 v[240:241], v[240:241], v[248:249], v[246:247]
	v_pk_mul_f32 v[238:239], v[230:231], v[238:239]
	v_pk_mul_f32 v[240:241], v[232:233], v[240:241]
	v_exp_f32_e32 v238, v238
	v_exp_f32_e32 v239, v239
	v_exp_f32_e32 v240, v240
	v_exp_f32_e32 v241, v241
	v_pk_add_f32 v[238:239], v[238:239], 1.0 op_sel_hi:[1,0]
	v_pk_add_f32 v[240:241], v[240:241], 1.0 op_sel_hi:[1,0]
	v_rcp_f32_e32 v238, v238
	v_rcp_f32_e32 v239, v239
	v_rcp_f32_e32 v240, v240
	v_rcp_f32_e32 v241, v241
	v_pk_mul_f32 v[230:231], v[230:231], v[234:235]
	v_pk_mul_f32 v[232:233], v[232:233], v[236:237]
	v_pk_mul_f32 v[238:239], v[230:231], v[238:239]
	v_pk_mul_f32 v[240:241], v[232:233], v[240:241]
	v_cvt_pk_bf16_f32 v212, v238, v239
	v_cvt_pk_bf16_f32 v213, v240, v241
	s_mov_b64 vcc, s[30:31]
	s_nop 0
	v_mov_b32_dpp v214, v212 quad_perm:[1,0,3,2] row_mask:0xf bank_mask:0xf
	v_mov_b32_dpp v215, v213 quad_perm:[1,0,3,2] row_mask:0xf bank_mask:0xf
	v_perm_b32 v216, v214, v212, v253
	v_perm_b32 v217, v215, v213, v253
	s_nop 1
	v_mov_b32_dpp v218, v216 quad_perm:[2,3,0,1] row_mask:0xf bank_mask:0xf
	v_mov_b32_dpp v219, v217 quad_perm:[2,3,0,1] row_mask:0xf bank_mask:0xf
	v_cndmask_b32_e32 v176, v216, v219, vcc
	v_cndmask_b32_e32 v177, v218, v217, vcc
	s_waitcnt lgkmcnt(0)
	s_mov_b64 vcc, s[28:29]
	v_cndmask_b32_e32 v208, v110, v142, vcc
	v_cndmask_b32_e32 v209, v111, v143, vcc
	v_cndmask_b32_e32 v210, v98, v138, vcc
	v_cndmask_b32_e32 v211, v99, v139, vcc
	ds_bpermute_b32 v200, v252, v208
	ds_bpermute_b32 v201, v252, v209
	ds_bpermute_b32 v202, v252, v210
	ds_bpermute_b32 v203, v252, v211
	v_pk_fma_f32 v[230:231], v[44:45], v[124:125], v[128:129] op_sel_hi:[1,0,0]
	v_pk_fma_f32 v[232:233], v[46:47], v[124:125], v[128:129] op_sel_hi:[1,0,0]
	v_fmac_f32_e32 v230, v205, v125
	v_fmac_f32_e32 v231, v44, v125
	v_fmac_f32_e32 v232, v45, v125
	v_fmac_f32_e32 v233, v46, v125
	v_pk_fma_f32 v[230:231], v[204:205], v[126:127], v[230:231] op_sel_hi:[1,0,1]
	v_pk_fma_f32 v[232:233], v[44:45], v[126:127], v[232:233] op_sel_hi:[1,0,1]
	v_pk_fma_f32 v[234:235], v[40:41], v[130:131], v[134:135] op_sel_hi:[1,0,0]
	v_pk_fma_f32 v[236:237], v[42:43], v[130:131], v[134:135] op_sel_hi:[1,0,0]
	v_fmac_f32_e32 v234, v207, v131
	v_fmac_f32_e32 v235, v40, v131
	v_fmac_f32_e32 v236, v41, v131
	v_fmac_f32_e32 v237, v42, v131
	v_pk_fma_f32 v[234:235], v[206:207], v[132:133], v[234:235] op_sel_hi:[1,0,1]
	v_pk_fma_f32 v[236:237], v[40:41], v[132:133], v[236:237] op_sel_hi:[1,0,1]
	v_pk_mul_f32 v[238:239], v[230:231], v[230:231]
	v_pk_mul_f32 v[240:241], v[232:233], v[232:233]
	v_pk_fma_f32 v[238:239], v[238:239], v[248:249], v[246:247]
	v_pk_fma_f32 v[240:241], v[240:241], v[248:249], v[246:247]
	v_pk_mul_f32 v[238:239], v[230:231], v[238:239]
	v_pk_mul_f32 v[240:241], v[232:233], v[240:241]
	v_exp_f32_e32 v238, v238
	v_exp_f32_e32 v239, v239
	v_exp_f32_e32 v240, v240
	v_exp_f32_e32 v241, v241
	v_pk_add_f32 v[238:239], v[238:239], 1.0 op_sel_hi:[1,0]
	v_pk_add_f32 v[240:241], v[240:241], 1.0 op_sel_hi:[1,0]
	v_rcp_f32_e32 v238, v238
	v_rcp_f32_e32 v239, v239
	v_rcp_f32_e32 v240, v240
	v_rcp_f32_e32 v241, v241
	v_pk_mul_f32 v[230:231], v[230:231], v[234:235]
	v_pk_mul_f32 v[232:233], v[232:233], v[236:237]
	v_pk_mul_f32 v[238:239], v[230:231], v[238:239]
	v_pk_mul_f32 v[240:241], v[232:233], v[240:241]
	v_cvt_pk_bf16_f32 v212, v238, v239
	v_cvt_pk_bf16_f32 v213, v240, v241
	s_mov_b64 vcc, s[30:31]
	s_nop 0
	v_mov_b32_dpp v214, v212 quad_perm:[1,0,3,2] row_mask:0xf bank_mask:0xf
	v_mov_b32_dpp v215, v213 quad_perm:[1,0,3,2] row_mask:0xf bank_mask:0xf
	v_perm_b32 v216, v214, v212, v253
	v_perm_b32 v217, v215, v213, v253
	s_nop 1
	v_mov_b32_dpp v218, v216 quad_perm:[2,3,0,1] row_mask:0xf bank_mask:0xf
	v_mov_b32_dpp v219, v217 quad_perm:[2,3,0,1] row_mask:0xf bank_mask:0xf
	v_cndmask_b32_e32 v178, v216, v219, vcc
	v_cndmask_b32_e32 v179, v218, v217, vcc
	s_movk_i32 s15, 0xfe2
	v_cmp_gt_i32_e64 s[24:25], s15, v251
	s_add_u32 s84, s58, 0x29400
	s_addc_u32 s85, s59, 0
	s_mov_b64 exec, s[24:25]
	global_store_dwordx4 v250, v[176:179], s[84:85] nt
	s_mov_b64 exec, -1
	s_nop 0
	s_waitcnt lgkmcnt(0)
	s_mov_b64 vcc, s[28:29]
	v_cndmask_b32_e32 v208, v38, v46, vcc
	v_cndmask_b32_e32 v209, v39, v47, vcc
	v_cndmask_b32_e32 v210, v34, v42, vcc
	v_cndmask_b32_e32 v211, v35, v43, vcc
	ds_bpermute_b32 v204, v252, v208
	ds_bpermute_b32 v205, v252, v209
	ds_bpermute_b32 v206, v252, v210
	ds_bpermute_b32 v207, v252, v211
	v_pk_fma_f32 v[230:231], v[108:109], v[112:113], v[116:117] op_sel_hi:[1,0,0]
	v_pk_fma_f32 v[232:233], v[110:111], v[112:113], v[116:117] op_sel_hi:[1,0,0]
	v_fmac_f32_e32 v230, v201, v113
	v_fmac_f32_e32 v231, v108, v113
	v_fmac_f32_e32 v232, v109, v113
	v_fmac_f32_e32 v233, v110, v113
	v_pk_fma_f32 v[230:231], v[200:201], v[114:115], v[230:231] op_sel_hi:[1,0,1]
	v_pk_fma_f32 v[232:233], v[108:109], v[114:115], v[232:233] op_sel_hi:[1,0,1]
	v_pk_fma_f32 v[234:235], v[96:97], v[118:119], v[122:123] op_sel_hi:[1,0,0]
	v_pk_fma_f32 v[236:237], v[98:99], v[118:119], v[122:123] op_sel_hi:[1,0,0]
	v_fmac_f32_e32 v234, v203, v119
	v_fmac_f32_e32 v235, v96, v119
	v_fmac_f32_e32 v236, v97, v119
	v_fmac_f32_e32 v237, v98, v119
	v_pk_fma_f32 v[234:235], v[202:203], v[120:121], v[234:235] op_sel_hi:[1,0,1]
	v_pk_fma_f32 v[236:237], v[96:97], v[120:121], v[236:237] op_sel_hi:[1,0,1]
	v_pk_mul_f32 v[238:239], v[230:231], v[230:231]
	v_pk_mul_f32 v[240:241], v[232:233], v[232:233]
	v_pk_fma_f32 v[238:239], v[238:239], v[248:249], v[246:247]
	v_pk_fma_f32 v[240:241], v[240:241], v[248:249], v[246:247]
	v_pk_mul_f32 v[238:239], v[230:231], v[238:239]
	v_pk_mul_f32 v[240:241], v[232:233], v[240:241]
	v_exp_f32_e32 v238, v238
	v_exp_f32_e32 v239, v239
	v_exp_f32_e32 v240, v240
	v_exp_f32_e32 v241, v241
	v_pk_add_f32 v[238:239], v[238:239], 1.0 op_sel_hi:[1,0]
	v_pk_add_f32 v[240:241], v[240:241], 1.0 op_sel_hi:[1,0]
	v_rcp_f32_e32 v238, v238
	v_rcp_f32_e32 v239, v239
	v_rcp_f32_e32 v240, v240
	v_rcp_f32_e32 v241, v241
	v_pk_mul_f32 v[230:231], v[230:231], v[234:235]
	v_pk_mul_f32 v[232:233], v[232:233], v[236:237]
	v_pk_mul_f32 v[238:239], v[230:231], v[238:239]
	v_pk_mul_f32 v[240:241], v[232:233], v[240:241]
	v_cvt_pk_bf16_f32 v212, v238, v239
	v_cvt_pk_bf16_f32 v213, v240, v241
	s_mov_b64 vcc, s[30:31]
	s_nop 0
	v_mov_b32_dpp v214, v212 quad_perm:[1,0,3,2] row_mask:0xf bank_mask:0xf
	v_mov_b32_dpp v215, v213 quad_perm:[1,0,3,2] row_mask:0xf bank_mask:0xf
	v_perm_b32 v216, v214, v212, v253
	v_perm_b32 v217, v215, v213, v253
	s_nop 1
	v_mov_b32_dpp v218, v216 quad_perm:[2,3,0,1] row_mask:0xf bank_mask:0xf
	v_mov_b32_dpp v219, v217 quad_perm:[2,3,0,1] row_mask:0xf bank_mask:0xf
	v_cndmask_b32_e32 v180, v216, v219, vcc
	v_cndmask_b32_e32 v181, v218, v217, vcc
	s_waitcnt lgkmcnt(0)
	ds_bpermute_b32 v200, v252, v94
	ds_bpermute_b32 v201, v252, v95
	ds_bpermute_b32 v202, v252, v90
	ds_bpermute_b32 v203, v252, v91
	v_pk_fma_f32 v[230:231], v[36:37], v[124:125], v[128:129] op_sel_hi:[1,0,0]
	v_pk_fma_f32 v[232:233], v[38:39], v[124:125], v[128:129] op_sel_hi:[1,0,0]
	v_fmac_f32_e32 v230, v205, v125
	v_fmac_f32_e32 v231, v36, v125
	v_fmac_f32_e32 v232, v37, v125
	v_fmac_f32_e32 v233, v38, v125
	v_pk_fma_f32 v[230:231], v[204:205], v[126:127], v[230:231] op_sel_hi:[1,0,1]
	v_pk_fma_f32 v[232:233], v[36:37], v[126:127], v[232:233] op_sel_hi:[1,0,1]
	v_pk_fma_f32 v[234:235], v[32:33], v[130:131], v[134:135] op_sel_hi:[1,0,0]
	v_pk_fma_f32 v[236:237], v[34:35], v[130:131], v[134:135] op_sel_hi:[1,0,0]
	v_fmac_f32_e32 v234, v207, v131
	v_fmac_f32_e32 v235, v32, v131
	v_fmac_f32_e32 v236, v33, v131
	v_fmac_f32_e32 v237, v34, v131
	v_pk_fma_f32 v[234:235], v[206:207], v[132:133], v[234:235] op_sel_hi:[1,0,1]
	v_pk_fma_f32 v[236:237], v[32:33], v[132:133], v[236:237] op_sel_hi:[1,0,1]
	v_pk_mul_f32 v[238:239], v[230:231], v[230:231]
	v_pk_mul_f32 v[240:241], v[232:233], v[232:233]
	v_pk_fma_f32 v[238:239], v[238:239], v[248:249], v[246:247]
	v_pk_fma_f32 v[240:241], v[240:241], v[248:249], v[246:247]
	v_pk_mul_f32 v[238:239], v[230:231], v[238:239]
	v_pk_mul_f32 v[240:241], v[232:233], v[240:241]
	v_exp_f32_e32 v238, v238
	v_exp_f32_e32 v239, v239
	v_exp_f32_e32 v240, v240
	v_exp_f32_e32 v241, v241
	v_pk_add_f32 v[238:239], v[238:239], 1.0 op_sel_hi:[1,0]
	v_pk_add_f32 v[240:241], v[240:241], 1.0 op_sel_hi:[1,0]
	v_rcp_f32_e32 v238, v238
	v_rcp_f32_e32 v239, v239
	v_rcp_f32_e32 v240, v240
	v_rcp_f32_e32 v241, v241
	v_pk_mul_f32 v[230:231], v[230:231], v[234:235]
	v_pk_mul_f32 v[232:233], v[232:233], v[236:237]
	v_pk_mul_f32 v[238:239], v[230:231], v[238:239]
	v_pk_mul_f32 v[240:241], v[232:233], v[240:241]
	v_cvt_pk_bf16_f32 v212, v238, v239
	v_cvt_pk_bf16_f32 v213, v240, v241
	s_mov_b64 vcc, s[30:31]
	s_nop 0
	v_mov_b32_dpp v214, v212 quad_perm:[1,0,3,2] row_mask:0xf bank_mask:0xf
	v_mov_b32_dpp v215, v213 quad_perm:[1,0,3,2] row_mask:0xf bank_mask:0xf
	v_perm_b32 v216, v214, v212, v253
	v_perm_b32 v217, v215, v213, v253
	s_nop 1
	v_mov_b32_dpp v218, v216 quad_perm:[2,3,0,1] row_mask:0xf bank_mask:0xf
	v_mov_b32_dpp v219, v217 quad_perm:[2,3,0,1] row_mask:0xf bank_mask:0xf
	v_cndmask_b32_e32 v182, v216, v219, vcc
	v_cndmask_b32_e32 v183, v218, v217, vcc
	s_movk_i32 s15, 0xfd2
	v_cmp_gt_i32_e64 s[24:25], s15, v251
	s_add_u32 s84, s58, 0x3f400
	s_addc_u32 s85, s59, 0
	s_mov_b64 exec, s[24:25]
	global_store_dwordx4 v250, v[180:183], s[84:85] nt
	s_mov_b64 exec, -1
	s_nop 0
	s_waitcnt lgkmcnt(0)
	ds_bpermute_b32 v204, v252, v30
	ds_bpermute_b32 v205, v252, v31
	ds_bpermute_b32 v206, v252, v26
	ds_bpermute_b32 v207, v252, v27
	v_pk_fma_f32 v[230:231], v[92:93], v[112:113], v[116:117] op_sel_hi:[1,0,0]
	v_pk_fma_f32 v[232:233], v[94:95], v[112:113], v[116:117] op_sel_hi:[1,0,0]
	v_fmac_f32_e32 v230, v201, v113
	v_fmac_f32_e32 v231, v92, v113
	v_fmac_f32_e32 v232, v93, v113
	v_fmac_f32_e32 v233, v94, v113
	v_pk_fma_f32 v[230:231], v[200:201], v[114:115], v[230:231] op_sel_hi:[1,0,1]
	v_pk_fma_f32 v[232:233], v[92:93], v[114:115], v[232:233] op_sel_hi:[1,0,1]
	v_pk_fma_f32 v[234:235], v[88:89], v[118:119], v[122:123] op_sel_hi:[1,0,0]
	v_pk_fma_f32 v[236:237], v[90:91], v[118:119], v[122:123] op_sel_hi:[1,0,0]
	v_fmac_f32_e32 v234, v203, v119
	v_fmac_f32_e32 v235, v88, v119
	v_fmac_f32_e32 v236, v89, v119
	v_fmac_f32_e32 v237, v90, v119
	v_pk_fma_f32 v[234:235], v[202:203], v[120:121], v[234:235] op_sel_hi:[1,0,1]
	v_pk_fma_f32 v[236:237], v[88:89], v[120:121], v[236:237] op_sel_hi:[1,0,1]
	v_pk_mul_f32 v[238:239], v[230:231], v[230:231]
	v_pk_mul_f32 v[240:241], v[232:233], v[232:233]
	v_pk_fma_f32 v[238:239], v[238:239], v[248:249], v[246:247]
	v_pk_fma_f32 v[240:241], v[240:241], v[248:249], v[246:247]
	v_pk_mul_f32 v[238:239], v[230:231], v[238:239]
	v_pk_mul_f32 v[240:241], v[232:233], v[240:241]
	v_exp_f32_e32 v238, v238
	v_exp_f32_e32 v239, v239
	v_exp_f32_e32 v240, v240
	v_exp_f32_e32 v241, v241
	v_pk_add_f32 v[238:239], v[238:239], 1.0 op_sel_hi:[1,0]
	v_pk_add_f32 v[240:241], v[240:241], 1.0 op_sel_hi:[1,0]
	v_rcp_f32_e32 v238, v238
	v_rcp_f32_e32 v239, v239
	v_rcp_f32_e32 v240, v240
	v_rcp_f32_e32 v241, v241
	v_pk_mul_f32 v[230:231], v[230:231], v[234:235]
	v_pk_mul_f32 v[232:233], v[232:233], v[236:237]
	v_pk_mul_f32 v[238:239], v[230:231], v[238:239]
	v_pk_mul_f32 v[240:241], v[232:233], v[240:241]
	v_cvt_pk_bf16_f32 v212, v238, v239
	v_cvt_pk_bf16_f32 v213, v240, v241
	s_mov_b64 vcc, s[30:31]
	s_nop 0
	v_mov_b32_dpp v214, v212 quad_perm:[1,0,3,2] row_mask:0xf bank_mask:0xf
	v_mov_b32_dpp v215, v213 quad_perm:[1,0,3,2] row_mask:0xf bank_mask:0xf
	v_perm_b32 v216, v214, v212, v253
	v_perm_b32 v217, v215, v213, v253
	s_nop 1
	v_mov_b32_dpp v218, v216 quad_perm:[2,3,0,1] row_mask:0xf bank_mask:0xf
	v_mov_b32_dpp v219, v217 quad_perm:[2,3,0,1] row_mask:0xf bank_mask:0xf
	v_cndmask_b32_e32 v176, v216, v219, vcc
	v_cndmask_b32_e32 v177, v218, v217, vcc
	s_waitcnt lgkmcnt(0)
	s_mov_b64 vcc, s[28:29]
	v_cndmask_b32_e32 v208, v86, v94, vcc
	v_cndmask_b32_e32 v209, v87, v95, vcc
	v_cndmask_b32_e32 v210, v82, v90, vcc
	v_cndmask_b32_e32 v211, v83, v91, vcc
	ds_bpermute_b32 v200, v252, v208
	ds_bpermute_b32 v201, v252, v209
	ds_bpermute_b32 v202, v252, v210
	ds_bpermute_b32 v203, v252, v211
	v_pk_fma_f32 v[230:231], v[28:29], v[124:125], v[128:129] op_sel_hi:[1,0,0]
	v_pk_fma_f32 v[232:233], v[30:31], v[124:125], v[128:129] op_sel_hi:[1,0,0]
	v_fmac_f32_e32 v230, v205, v125
	v_fmac_f32_e32 v231, v28, v125
	v_fmac_f32_e32 v232, v29, v125
	v_fmac_f32_e32 v233, v30, v125
	v_pk_fma_f32 v[230:231], v[204:205], v[126:127], v[230:231] op_sel_hi:[1,0,1]
	v_pk_fma_f32 v[232:233], v[28:29], v[126:127], v[232:233] op_sel_hi:[1,0,1]
	v_pk_fma_f32 v[234:235], v[24:25], v[130:131], v[134:135] op_sel_hi:[1,0,0]
	v_pk_fma_f32 v[236:237], v[26:27], v[130:131], v[134:135] op_sel_hi:[1,0,0]
	v_fmac_f32_e32 v234, v207, v131
	v_fmac_f32_e32 v235, v24, v131
	v_fmac_f32_e32 v236, v25, v131
	v_fmac_f32_e32 v237, v26, v131
	v_pk_fma_f32 v[234:235], v[206:207], v[132:133], v[234:235] op_sel_hi:[1,0,1]
	v_pk_fma_f32 v[236:237], v[24:25], v[132:133], v[236:237] op_sel_hi:[1,0,1]
	v_pk_mul_f32 v[238:239], v[230:231], v[230:231]
	v_pk_mul_f32 v[240:241], v[232:233], v[232:233]
	v_pk_fma_f32 v[238:239], v[238:239], v[248:249], v[246:247]
	v_pk_fma_f32 v[240:241], v[240:241], v[248:249], v[246:247]
	v_pk_mul_f32 v[238:239], v[230:231], v[238:239]
	v_pk_mul_f32 v[240:241], v[232:233], v[240:241]
	v_exp_f32_e32 v238, v238
	v_exp_f32_e32 v239, v239
	v_exp_f32_e32 v240, v240
	v_exp_f32_e32 v241, v241
	v_pk_add_f32 v[238:239], v[238:239], 1.0 op_sel_hi:[1,0]
	v_pk_add_f32 v[240:241], v[240:241], 1.0 op_sel_hi:[1,0]
	v_rcp_f32_e32 v238, v238
	v_rcp_f32_e32 v239, v239
	v_rcp_f32_e32 v240, v240
	v_rcp_f32_e32 v241, v241
	v_pk_mul_f32 v[230:231], v[230:231], v[234:235]
	v_pk_mul_f32 v[232:233], v[232:233], v[236:237]
	v_pk_mul_f32 v[238:239], v[230:231], v[238:239]
	v_pk_mul_f32 v[240:241], v[232:233], v[240:241]
	v_cvt_pk_bf16_f32 v212, v238, v239
	v_cvt_pk_bf16_f32 v213, v240, v241
	s_mov_b64 vcc, s[30:31]
	s_nop 0
	v_mov_b32_dpp v214, v212 quad_perm:[1,0,3,2] row_mask:0xf bank_mask:0xf
	v_mov_b32_dpp v215, v213 quad_perm:[1,0,3,2] row_mask:0xf bank_mask:0xf
	v_perm_b32 v216, v214, v212, v253
	v_perm_b32 v217, v215, v213, v253
	s_nop 1
	v_mov_b32_dpp v218, v216 quad_perm:[2,3,0,1] row_mask:0xf bank_mask:0xf
	v_mov_b32_dpp v219, v217 quad_perm:[2,3,0,1] row_mask:0xf bank_mask:0xf
	v_cndmask_b32_e32 v178, v216, v219, vcc
	v_cndmask_b32_e32 v179, v218, v217, vcc
	s_movk_i32 s15, 0xf86
	v_cmp_gt_i32_e64 s[24:25], s15, v251
	s_add_u32 s84, s58, 0xa7c00
	s_addc_u32 s85, s59, 0
	s_and_b64 s[24:25], s[24:25], s[36:37]
	s_mov_b64 exec, s[24:25]
	global_store_dwordx4 v250, v[176:179], s[84:85] nt
	s_mov_b64 exec, -1
	s_nop 0
	s_waitcnt lgkmcnt(0)
	s_mov_b64 vcc, s[28:29]
	v_cndmask_b32_e32 v208, v22, v30, vcc
	v_cndmask_b32_e32 v209, v23, v31, vcc
	v_cndmask_b32_e32 v210, v18, v26, vcc
	v_cndmask_b32_e32 v211, v19, v27, vcc
	ds_bpermute_b32 v204, v252, v208
	ds_bpermute_b32 v205, v252, v209
	ds_bpermute_b32 v206, v252, v210
	ds_bpermute_b32 v207, v252, v211
	v_pk_fma_f32 v[230:231], v[84:85], v[112:113], v[116:117] op_sel_hi:[1,0,0]
	v_pk_fma_f32 v[232:233], v[86:87], v[112:113], v[116:117] op_sel_hi:[1,0,0]
	v_fmac_f32_e32 v230, v201, v113
	v_fmac_f32_e32 v231, v84, v113
	v_fmac_f32_e32 v232, v85, v113
	v_fmac_f32_e32 v233, v86, v113
	v_pk_fma_f32 v[230:231], v[200:201], v[114:115], v[230:231] op_sel_hi:[1,0,1]
	v_pk_fma_f32 v[232:233], v[84:85], v[114:115], v[232:233] op_sel_hi:[1,0,1]
	v_pk_fma_f32 v[234:235], v[80:81], v[118:119], v[122:123] op_sel_hi:[1,0,0]
	v_pk_fma_f32 v[236:237], v[82:83], v[118:119], v[122:123] op_sel_hi:[1,0,0]
	v_fmac_f32_e32 v234, v203, v119
	v_fmac_f32_e32 v235, v80, v119
	v_fmac_f32_e32 v236, v81, v119
	v_fmac_f32_e32 v237, v82, v119
	v_pk_fma_f32 v[234:235], v[202:203], v[120:121], v[234:235] op_sel_hi:[1,0,1]
	v_pk_fma_f32 v[236:237], v[80:81], v[120:121], v[236:237] op_sel_hi:[1,0,1]
	v_pk_mul_f32 v[238:239], v[230:231], v[230:231]
	v_pk_mul_f32 v[240:241], v[232:233], v[232:233]
	v_pk_fma_f32 v[238:239], v[238:239], v[248:249], v[246:247]
	v_pk_fma_f32 v[240:241], v[240:241], v[248:249], v[246:247]
	v_pk_mul_f32 v[238:239], v[230:231], v[238:239]
	v_pk_mul_f32 v[240:241], v[232:233], v[240:241]
	v_exp_f32_e32 v238, v238
	v_exp_f32_e32 v239, v239
	v_exp_f32_e32 v240, v240
	v_exp_f32_e32 v241, v241
	v_pk_add_f32 v[238:239], v[238:239], 1.0 op_sel_hi:[1,0]
	v_pk_add_f32 v[240:241], v[240:241], 1.0 op_sel_hi:[1,0]
	v_rcp_f32_e32 v238, v238
	v_rcp_f32_e32 v239, v239
	v_rcp_f32_e32 v240, v240
	v_rcp_f32_e32 v241, v241
	v_pk_mul_f32 v[230:231], v[230:231], v[234:235]
	v_pk_mul_f32 v[232:233], v[232:233], v[236:237]
	v_pk_mul_f32 v[238:239], v[230:231], v[238:239]
	v_pk_mul_f32 v[240:241], v[232:233], v[240:241]
	v_cvt_pk_bf16_f32 v212, v238, v239
	v_cvt_pk_bf16_f32 v213, v240, v241
	s_mov_b64 vcc, s[30:31]
	s_nop 0
	v_mov_b32_dpp v214, v212 quad_perm:[1,0,3,2] row_mask:0xf bank_mask:0xf
	v_mov_b32_dpp v215, v213 quad_perm:[1,0,3,2] row_mask:0xf bank_mask:0xf
	v_perm_b32 v216, v214, v212, v253
	v_perm_b32 v217, v215, v213, v253
	s_nop 1
	v_mov_b32_dpp v218, v216 quad_perm:[2,3,0,1] row_mask:0xf bank_mask:0xf
	v_mov_b32_dpp v219, v217 quad_perm:[2,3,0,1] row_mask:0xf bank_mask:0xf
	v_cndmask_b32_e32 v180, v216, v219, vcc
	v_cndmask_b32_e32 v181, v218, v217, vcc
	s_waitcnt lgkmcnt(0)
	s_mov_b64 vcc, s[28:29]
	v_cndmask_b32_e32 v208, v78, v86, vcc
	v_cndmask_b32_e32 v209, v79, v87, vcc
	v_cndmask_b32_e32 v210, v74, v82, vcc
	v_cndmask_b32_e32 v211, v75, v83, vcc
	ds_bpermute_b32 v200, v252, v208
	ds_bpermute_b32 v201, v252, v209
	ds_bpermute_b32 v202, v252, v210
	ds_bpermute_b32 v203, v252, v211
	v_pk_fma_f32 v[230:231], v[20:21], v[124:125], v[128:129] op_sel_hi:[1,0,0]
	v_pk_fma_f32 v[232:233], v[22:23], v[124:125], v[128:129] op_sel_hi:[1,0,0]
	v_fmac_f32_e32 v230, v205, v125
	v_fmac_f32_e32 v231, v20, v125
	v_fmac_f32_e32 v232, v21, v125
	v_fmac_f32_e32 v233, v22, v125
	v_pk_fma_f32 v[230:231], v[204:205], v[126:127], v[230:231] op_sel_hi:[1,0,1]
	v_pk_fma_f32 v[232:233], v[20:21], v[126:127], v[232:233] op_sel_hi:[1,0,1]
	v_pk_fma_f32 v[234:235], v[16:17], v[130:131], v[134:135] op_sel_hi:[1,0,0]
	v_pk_fma_f32 v[236:237], v[18:19], v[130:131], v[134:135] op_sel_hi:[1,0,0]
	v_fmac_f32_e32 v234, v207, v131
	v_fmac_f32_e32 v235, v16, v131
	v_fmac_f32_e32 v236, v17, v131
	v_fmac_f32_e32 v237, v18, v131
	v_pk_fma_f32 v[234:235], v[206:207], v[132:133], v[234:235] op_sel_hi:[1,0,1]
	v_pk_fma_f32 v[236:237], v[16:17], v[132:133], v[236:237] op_sel_hi:[1,0,1]
	v_pk_mul_f32 v[238:239], v[230:231], v[230:231]
	v_pk_mul_f32 v[240:241], v[232:233], v[232:233]
	v_pk_fma_f32 v[238:239], v[238:239], v[248:249], v[246:247]
	v_pk_fma_f32 v[240:241], v[240:241], v[248:249], v[246:247]
	v_pk_mul_f32 v[238:239], v[230:231], v[238:239]
	v_pk_mul_f32 v[240:241], v[232:233], v[240:241]
	v_exp_f32_e32 v238, v238
	v_exp_f32_e32 v239, v239
	v_exp_f32_e32 v240, v240
	v_exp_f32_e32 v241, v241
	v_pk_add_f32 v[238:239], v[238:239], 1.0 op_sel_hi:[1,0]
	v_pk_add_f32 v[240:241], v[240:241], 1.0 op_sel_hi:[1,0]
	v_rcp_f32_e32 v238, v238
	v_rcp_f32_e32 v239, v239
	v_rcp_f32_e32 v240, v240
	v_rcp_f32_e32 v241, v241
	v_pk_mul_f32 v[230:231], v[230:231], v[234:235]
	v_pk_mul_f32 v[232:233], v[232:233], v[236:237]
	v_pk_mul_f32 v[238:239], v[230:231], v[238:239]
	v_pk_mul_f32 v[240:241], v[232:233], v[240:241]
	v_cvt_pk_bf16_f32 v212, v238, v239
	v_cvt_pk_bf16_f32 v213, v240, v241
	s_mov_b64 vcc, s[30:31]
	s_nop 0
	v_mov_b32_dpp v214, v212 quad_perm:[1,0,3,2] row_mask:0xf bank_mask:0xf
	v_mov_b32_dpp v215, v213 quad_perm:[1,0,3,2] row_mask:0xf bank_mask:0xf
	v_perm_b32 v216, v214, v212, v253
	v_perm_b32 v217, v215, v213, v253
	s_nop 1
	v_mov_b32_dpp v218, v216 quad_perm:[2,3,0,1] row_mask:0xf bank_mask:0xf
	v_mov_b32_dpp v219, v217 quad_perm:[2,3,0,1] row_mask:0xf bank_mask:0xf
	v_cndmask_b32_e32 v182, v216, v219, vcc
	v_cndmask_b32_e32 v183, v218, v217, vcc
	s_movk_i32 s15, 0xf76
	v_cmp_gt_i32_e64 s[24:25], s15, v251
	s_add_u32 s84, s58, 0xbdc00
	s_addc_u32 s85, s59, 0
	s_mov_b64 exec, s[24:25]
	global_store_dwordx4 v250, v[180:183], s[84:85] nt
	s_mov_b64 exec, -1
	s_nop 0
	s_waitcnt lgkmcnt(0)
	s_mov_b64 vcc, s[28:29]
	v_cndmask_b32_e32 v208, v14, v22, vcc
	v_cndmask_b32_e32 v209, v15, v23, vcc
	v_cndmask_b32_e32 v210, v10, v18, vcc
	v_cndmask_b32_e32 v211, v11, v19, vcc
	ds_bpermute_b32 v204, v252, v208
	ds_bpermute_b32 v205, v252, v209
	ds_bpermute_b32 v206, v252, v210
	ds_bpermute_b32 v207, v252, v211
	v_pk_fma_f32 v[230:231], v[76:77], v[112:113], v[116:117] op_sel_hi:[1,0,0]
	v_pk_fma_f32 v[232:233], v[78:79], v[112:113], v[116:117] op_sel_hi:[1,0,0]
	v_fmac_f32_e32 v230, v201, v113
	v_fmac_f32_e32 v231, v76, v113
	v_fmac_f32_e32 v232, v77, v113
	v_fmac_f32_e32 v233, v78, v113
	v_pk_fma_f32 v[230:231], v[200:201], v[114:115], v[230:231] op_sel_hi:[1,0,1]
	v_pk_fma_f32 v[232:233], v[76:77], v[114:115], v[232:233] op_sel_hi:[1,0,1]
	v_pk_fma_f32 v[234:235], v[72:73], v[118:119], v[122:123] op_sel_hi:[1,0,0]
	v_pk_fma_f32 v[236:237], v[74:75], v[118:119], v[122:123] op_sel_hi:[1,0,0]
	v_fmac_f32_e32 v234, v203, v119
	v_fmac_f32_e32 v235, v72, v119
	v_fmac_f32_e32 v236, v73, v119
	v_fmac_f32_e32 v237, v74, v119
	v_pk_fma_f32 v[234:235], v[202:203], v[120:121], v[234:235] op_sel_hi:[1,0,1]
	v_pk_fma_f32 v[236:237], v[72:73], v[120:121], v[236:237] op_sel_hi:[1,0,1]
	v_pk_mul_f32 v[238:239], v[230:231], v[230:231]
	v_pk_mul_f32 v[240:241], v[232:233], v[232:233]
	v_pk_fma_f32 v[238:239], v[238:239], v[248:249], v[246:247]
	v_pk_fma_f32 v[240:241], v[240:241], v[248:249], v[246:247]
	v_pk_mul_f32 v[238:239], v[230:231], v[238:239]
	v_pk_mul_f32 v[240:241], v[232:233], v[240:241]
	v_exp_f32_e32 v238, v238
	v_exp_f32_e32 v239, v239
	v_exp_f32_e32 v240, v240
	v_exp_f32_e32 v241, v241
	v_pk_add_f32 v[238:239], v[238:239], 1.0 op_sel_hi:[1,0]
	v_pk_add_f32 v[240:241], v[240:241], 1.0 op_sel_hi:[1,0]
	v_rcp_f32_e32 v238, v238
	v_rcp_f32_e32 v239, v239
	v_rcp_f32_e32 v240, v240
	v_rcp_f32_e32 v241, v241
	v_pk_mul_f32 v[230:231], v[230:231], v[234:235]
	v_pk_mul_f32 v[232:233], v[232:233], v[236:237]
	v_pk_mul_f32 v[238:239], v[230:231], v[238:239]
	v_pk_mul_f32 v[240:241], v[232:233], v[240:241]
	v_cvt_pk_bf16_f32 v212, v238, v239
	v_cvt_pk_bf16_f32 v213, v240, v241
	s_mov_b64 vcc, s[30:31]
	s_nop 0
	v_mov_b32_dpp v214, v212 quad_perm:[1,0,3,2] row_mask:0xf bank_mask:0xf
	v_mov_b32_dpp v215, v213 quad_perm:[1,0,3,2] row_mask:0xf bank_mask:0xf
	v_perm_b32 v216, v214, v212, v253
	v_perm_b32 v217, v215, v213, v253
	s_nop 1
	v_mov_b32_dpp v218, v216 quad_perm:[2,3,0,1] row_mask:0xf bank_mask:0xf
	v_mov_b32_dpp v219, v217 quad_perm:[2,3,0,1] row_mask:0xf bank_mask:0xf
	v_cndmask_b32_e32 v176, v216, v219, vcc
	v_cndmask_b32_e32 v177, v218, v217, vcc
	s_waitcnt lgkmcnt(0)
	s_mov_b64 vcc, s[28:29]
	v_cndmask_b32_e32 v208, v70, v78, vcc
	v_cndmask_b32_e32 v209, v71, v79, vcc
	v_cndmask_b32_e32 v210, v66, v74, vcc
	v_cndmask_b32_e32 v211, v67, v75, vcc
	ds_bpermute_b32 v200, v252, v208
	ds_bpermute_b32 v201, v252, v209
	ds_bpermute_b32 v202, v252, v210
	ds_bpermute_b32 v203, v252, v211
	v_pk_fma_f32 v[230:231], v[12:13], v[124:125], v[128:129] op_sel_hi:[1,0,0]
	v_pk_fma_f32 v[232:233], v[14:15], v[124:125], v[128:129] op_sel_hi:[1,0,0]
	v_fmac_f32_e32 v230, v205, v125
	v_fmac_f32_e32 v231, v12, v125
	v_fmac_f32_e32 v232, v13, v125
	v_fmac_f32_e32 v233, v14, v125
	v_pk_fma_f32 v[230:231], v[204:205], v[126:127], v[230:231] op_sel_hi:[1,0,1]
	v_pk_fma_f32 v[232:233], v[12:13], v[126:127], v[232:233] op_sel_hi:[1,0,1]
	v_pk_fma_f32 v[234:235], v[8:9], v[130:131], v[134:135] op_sel_hi:[1,0,0]
	v_pk_fma_f32 v[236:237], v[10:11], v[130:131], v[134:135] op_sel_hi:[1,0,0]
	v_fmac_f32_e32 v234, v207, v131
	v_fmac_f32_e32 v235, v8, v131
	v_fmac_f32_e32 v236, v9, v131
	v_fmac_f32_e32 v237, v10, v131
	v_pk_fma_f32 v[234:235], v[206:207], v[132:133], v[234:235] op_sel_hi:[1,0,1]
	v_pk_fma_f32 v[236:237], v[8:9], v[132:133], v[236:237] op_sel_hi:[1,0,1]
	v_pk_mul_f32 v[238:239], v[230:231], v[230:231]
	v_pk_mul_f32 v[240:241], v[232:233], v[232:233]
	v_pk_fma_f32 v[238:239], v[238:239], v[248:249], v[246:247]
	v_pk_fma_f32 v[240:241], v[240:241], v[248:249], v[246:247]
	v_pk_mul_f32 v[238:239], v[230:231], v[238:239]
	v_pk_mul_f32 v[240:241], v[232:233], v[240:241]
	v_exp_f32_e32 v238, v238
	v_exp_f32_e32 v239, v239
	v_exp_f32_e32 v240, v240
	v_exp_f32_e32 v241, v241
	v_pk_add_f32 v[238:239], v[238:239], 1.0 op_sel_hi:[1,0]
	v_pk_add_f32 v[240:241], v[240:241], 1.0 op_sel_hi:[1,0]
	v_rcp_f32_e32 v238, v238
	v_rcp_f32_e32 v239, v239
	v_rcp_f32_e32 v240, v240
	v_rcp_f32_e32 v241, v241
	v_pk_mul_f32 v[230:231], v[230:231], v[234:235]
	v_pk_mul_f32 v[232:233], v[232:233], v[236:237]
	v_pk_mul_f32 v[238:239], v[230:231], v[238:239]
	v_pk_mul_f32 v[240:241], v[232:233], v[240:241]
	v_cvt_pk_bf16_f32 v212, v238, v239
	v_cvt_pk_bf16_f32 v213, v240, v241
	s_mov_b64 vcc, s[30:31]
	s_nop 0
	v_mov_b32_dpp v214, v212 quad_perm:[1,0,3,2] row_mask:0xf bank_mask:0xf
	v_mov_b32_dpp v215, v213 quad_perm:[1,0,3,2] row_mask:0xf bank_mask:0xf
	v_perm_b32 v216, v214, v212, v253
	v_perm_b32 v217, v215, v213, v253
	s_nop 1
	v_mov_b32_dpp v218, v216 quad_perm:[2,3,0,1] row_mask:0xf bank_mask:0xf
	v_mov_b32_dpp v219, v217 quad_perm:[2,3,0,1] row_mask:0xf bank_mask:0xf
	v_cndmask_b32_e32 v178, v216, v219, vcc
	v_cndmask_b32_e32 v179, v218, v217, vcc
	s_movk_i32 s15, 0xf66
	v_cmp_gt_i32_e64 s[24:25], s15, v251
	s_add_u32 s84, s58, 0xd3c00
	s_addc_u32 s85, s59, 0
	s_mov_b64 exec, s[24:25]
	global_store_dwordx4 v250, v[176:179], s[84:85] nt
	s_mov_b64 exec, -1
	s_nop 0
	s_waitcnt lgkmcnt(0)
	s_mov_b64 vcc, s[28:29]
	v_cndmask_b32_e32 v208, v6, v14, vcc
	v_cndmask_b32_e32 v209, v7, v15, vcc
	v_cndmask_b32_e32 v210, v2, v10, vcc
	v_cndmask_b32_e32 v211, v3, v11, vcc
	ds_bpermute_b32 v204, v252, v208
	ds_bpermute_b32 v205, v252, v209
	ds_bpermute_b32 v206, v252, v210
	ds_bpermute_b32 v207, v252, v211
	v_pk_fma_f32 v[230:231], v[68:69], v[112:113], v[116:117] op_sel_hi:[1,0,0]
	v_pk_fma_f32 v[232:233], v[70:71], v[112:113], v[116:117] op_sel_hi:[1,0,0]
	v_fmac_f32_e32 v230, v201, v113
	v_fmac_f32_e32 v231, v68, v113
	v_fmac_f32_e32 v232, v69, v113
	v_fmac_f32_e32 v233, v70, v113
	v_pk_fma_f32 v[230:231], v[200:201], v[114:115], v[230:231] op_sel_hi:[1,0,1]
	v_pk_fma_f32 v[232:233], v[68:69], v[114:115], v[232:233] op_sel_hi:[1,0,1]
	v_pk_fma_f32 v[234:235], v[64:65], v[118:119], v[122:123] op_sel_hi:[1,0,0]
	v_pk_fma_f32 v[236:237], v[66:67], v[118:119], v[122:123] op_sel_hi:[1,0,0]
	v_fmac_f32_e32 v234, v203, v119
	v_fmac_f32_e32 v235, v64, v119
	v_fmac_f32_e32 v236, v65, v119
	v_fmac_f32_e32 v237, v66, v119
	v_pk_fma_f32 v[234:235], v[202:203], v[120:121], v[234:235] op_sel_hi:[1,0,1]
	v_pk_fma_f32 v[236:237], v[64:65], v[120:121], v[236:237] op_sel_hi:[1,0,1]
	v_pk_mul_f32 v[238:239], v[230:231], v[230:231]
	v_pk_mul_f32 v[240:241], v[232:233], v[232:233]
	v_pk_fma_f32 v[238:239], v[238:239], v[248:249], v[246:247]
	v_pk_fma_f32 v[240:241], v[240:241], v[248:249], v[246:247]
	v_pk_mul_f32 v[238:239], v[230:231], v[238:239]
	v_pk_mul_f32 v[240:241], v[232:233], v[240:241]
	v_exp_f32_e32 v238, v238
	v_exp_f32_e32 v239, v239
	v_exp_f32_e32 v240, v240
	v_exp_f32_e32 v241, v241
	v_pk_add_f32 v[238:239], v[238:239], 1.0 op_sel_hi:[1,0]
	v_pk_add_f32 v[240:241], v[240:241], 1.0 op_sel_hi:[1,0]
	v_rcp_f32_e32 v238, v238
	v_rcp_f32_e32 v239, v239
	v_rcp_f32_e32 v240, v240
	v_rcp_f32_e32 v241, v241
	v_pk_mul_f32 v[230:231], v[230:231], v[234:235]
	v_pk_mul_f32 v[232:233], v[232:233], v[236:237]
	v_pk_mul_f32 v[238:239], v[230:231], v[238:239]
	v_pk_mul_f32 v[240:241], v[232:233], v[240:241]
	v_cvt_pk_bf16_f32 v212, v238, v239
	v_cvt_pk_bf16_f32 v213, v240, v241
	s_mov_b64 vcc, s[30:31]
	s_nop 0
	v_mov_b32_dpp v214, v212 quad_perm:[1,0,3,2] row_mask:0xf bank_mask:0xf
	v_mov_b32_dpp v215, v213 quad_perm:[1,0,3,2] row_mask:0xf bank_mask:0xf
	v_perm_b32 v216, v214, v212, v253
	v_perm_b32 v217, v215, v213, v253
	s_nop 1
	v_mov_b32_dpp v218, v216 quad_perm:[2,3,0,1] row_mask:0xf bank_mask:0xf
	v_mov_b32_dpp v219, v217 quad_perm:[2,3,0,1] row_mask:0xf bank_mask:0xf
	v_cndmask_b32_e32 v180, v216, v219, vcc
	v_cndmask_b32_e32 v181, v218, v217, vcc
	s_waitcnt lgkmcnt(0)
	v_pk_fma_f32 v[230:231], v[4:5], v[124:125], v[128:129] op_sel_hi:[1,0,0]
	v_pk_fma_f32 v[232:233], v[6:7], v[124:125], v[128:129] op_sel_hi:[1,0,0]
	v_fmac_f32_e32 v230, v205, v125
	v_fmac_f32_e32 v231, v4, v125
	v_fmac_f32_e32 v232, v5, v125
	v_fmac_f32_e32 v233, v6, v125
	v_pk_fma_f32 v[230:231], v[204:205], v[126:127], v[230:231] op_sel_hi:[1,0,1]
	v_pk_fma_f32 v[232:233], v[4:5], v[126:127], v[232:233] op_sel_hi:[1,0,1]
	v_pk_fma_f32 v[234:235], v[0:1], v[130:131], v[134:135] op_sel_hi:[1,0,0]
	v_pk_fma_f32 v[236:237], v[2:3], v[130:131], v[134:135] op_sel_hi:[1,0,0]
	v_fmac_f32_e32 v234, v207, v131
	v_fmac_f32_e32 v235, v0, v131
	v_fmac_f32_e32 v236, v1, v131
	v_fmac_f32_e32 v237, v2, v131
	v_pk_fma_f32 v[234:235], v[206:207], v[132:133], v[234:235] op_sel_hi:[1,0,1]
	v_pk_fma_f32 v[236:237], v[0:1], v[132:133], v[236:237] op_sel_hi:[1,0,1]
	v_pk_mul_f32 v[238:239], v[230:231], v[230:231]
	v_pk_mul_f32 v[240:241], v[232:233], v[232:233]
	v_pk_fma_f32 v[238:239], v[238:239], v[248:249], v[246:247]
	v_pk_fma_f32 v[240:241], v[240:241], v[248:249], v[246:247]
	v_pk_mul_f32 v[238:239], v[230:231], v[238:239]
	v_pk_mul_f32 v[240:241], v[232:233], v[240:241]
	v_exp_f32_e32 v238, v238
	v_exp_f32_e32 v239, v239
	v_exp_f32_e32 v240, v240
	v_exp_f32_e32 v241, v241
	v_pk_add_f32 v[238:239], v[238:239], 1.0 op_sel_hi:[1,0]
	v_pk_add_f32 v[240:241], v[240:241], 1.0 op_sel_hi:[1,0]
	v_rcp_f32_e32 v238, v238
	v_rcp_f32_e32 v239, v239
	v_rcp_f32_e32 v240, v240
	v_rcp_f32_e32 v241, v241
	v_pk_mul_f32 v[230:231], v[230:231], v[234:235]
	v_pk_mul_f32 v[232:233], v[232:233], v[236:237]
	v_pk_mul_f32 v[238:239], v[230:231], v[238:239]
	v_pk_mul_f32 v[240:241], v[232:233], v[240:241]
	v_cvt_pk_bf16_f32 v212, v238, v239
	v_cvt_pk_bf16_f32 v213, v240, v241
	s_mov_b64 vcc, s[30:31]
	s_nop 0
	v_mov_b32_dpp v214, v212 quad_perm:[1,0,3,2] row_mask:0xf bank_mask:0xf
	v_mov_b32_dpp v215, v213 quad_perm:[1,0,3,2] row_mask:0xf bank_mask:0xf
	v_perm_b32 v216, v214, v212, v253
	v_perm_b32 v217, v215, v213, v253
	s_nop 1
	v_mov_b32_dpp v218, v216 quad_perm:[2,3,0,1] row_mask:0xf bank_mask:0xf
	v_mov_b32_dpp v219, v217 quad_perm:[2,3,0,1] row_mask:0xf bank_mask:0xf
	v_cndmask_b32_e32 v182, v216, v219, vcc
	v_cndmask_b32_e32 v183, v218, v217, vcc
	s_movk_i32 s15, 0xf56
	v_cmp_gt_i32_e64 s[24:25], s15, v251
	s_add_u32 s84, s58, 0xe9c00
	s_addc_u32 s85, s59, 0
	s_mov_b64 exec, s[24:25]
	global_store_dwordx4 v250, v[180:183], s[84:85] nt
	s_mov_b64 exec, -1
	s_nop 0
	s_mov_b64 s[0:1], -1
	s_branch .LBB0_619
	s_nop 0
	s_nop 0
	s_nop 0
	s_nop 0
	s_nop 0
	s_nop 0
	s_nop 0
	s_nop 0
	s_nop 0
	s_nop 0
	s_nop 0
	s_nop 0
	s_nop 0
	s_nop 0
	s_nop 0
	s_nop 0
	s_nop 0
	s_nop 0
	s_nop 0
	s_nop 0
	s_nop 0
	s_nop 0
	s_nop 0
	s_nop 0
	s_nop 0
	s_nop 0
	s_nop 0
	s_nop 0
	s_nop 0
	s_nop 0
	s_nop 0
	s_nop 0
	s_nop 0
	s_nop 0
	s_nop 0
	s_nop 0
	s_nop 0
	s_nop 0
	s_nop 0
	s_nop 0
	s_nop 0
	s_nop 0
	s_nop 0
	s_nop 0
	s_nop 0
	s_nop 0
	s_nop 0
	s_nop 0
	s_nop 0
	s_nop 0
	s_nop 0
	s_nop 0
	s_nop 0
	s_nop 0
	s_nop 0
	s_nop 0
	s_nop 0
	s_nop 0
	s_nop 0
	s_nop 0
	s_nop 0
	s_nop 0
	s_nop 0
	s_nop 0
	s_nop 0
	s_nop 0
	s_nop 0
	s_nop 0
	s_nop 0
	s_nop 0
	s_nop 0
	s_nop 0
	s_nop 0
	s_nop 0
	s_nop 0
	s_nop 0
	s_nop 0
	s_nop 0
	s_nop 0
	s_nop 0
	s_nop 0
	s_nop 0
	s_nop 0
	s_nop 0
	s_nop 0
	s_nop 0
	s_nop 0
	s_nop 0
	s_nop 0
	s_nop 0
	s_nop 0
	s_nop 0
	s_nop 0
	s_nop 0
	s_nop 0
	s_nop 0
	s_nop 0
	s_nop 0
	s_nop 0
	s_nop 0
	s_nop 0
	s_nop 0
	s_nop 0
	s_nop 0
	s_nop 0
	s_nop 0
	s_nop 0
	s_nop 0
	s_nop 0
	s_nop 0
	s_nop 0
	s_nop 0
	s_nop 0
	s_nop 0
	s_nop 0
	s_nop 0
	s_nop 0
	s_nop 0
	s_nop 0
	s_nop 0
	s_nop 0
	s_nop 0
	s_nop 0
	s_nop 0
	s_nop 0
	s_nop 0
	s_nop 0
	s_nop 0
	s_nop 0
	s_nop 0
	s_nop 0
	s_nop 0
	s_nop 0
	s_nop 0
	s_nop 0
	s_nop 0
	s_nop 0
	s_nop 0
	s_nop 0
	s_nop 0
	s_nop 0
	s_nop 0
	s_nop 0
	s_nop 0
	s_nop 0
	s_nop 0
	s_nop 0
	s_nop 0
	s_nop 0
	s_nop 0
	s_nop 0
	s_nop 0
	s_nop 0
	s_nop 0
	s_nop 0
	s_nop 0
	s_nop 0
	s_nop 0
	s_nop 0
	s_nop 0
	s_nop 0
	s_nop 0
	s_nop 0
	s_nop 0
	s_nop 0
	s_nop 0
	s_nop 0
	s_nop 0
	s_nop 0
	s_nop 0
	s_nop 0
	s_nop 0
	s_nop 0
	s_nop 0
	s_nop 0
	s_nop 0
	s_nop 0
	s_nop 0
	s_nop 0
	s_nop 0
	s_nop 0
	s_nop 0
	s_nop 0
	s_nop 0
	s_nop 0
	s_nop 0
	s_nop 0
	s_nop 0
	s_nop 0
	s_nop 0
	s_nop 0
	s_nop 0
	s_nop 0
	s_nop 0
	s_nop 0
	s_nop 0
	s_nop 0
	s_nop 0
	s_nop 0
	s_nop 0
	s_nop 0
	s_nop 0
	s_nop 0
	s_nop 0
	s_nop 0
	s_nop 0
	s_nop 0
	s_nop 0
	s_nop 0
	s_nop 0
	s_nop 0
	s_nop 0
.LBB0_619:
	s_or_b64 exec, exec, s[0:1]
	s_and_b64 vcc, exec, s[6:7]
	s_mov_b64 s[0:1], -1
	s_cbranch_vccnz .LBB0_578
	v_readlane_b32 s0, v254, 54
	v_readlane_b32 s1, v254, 55
	s_andn2_b64 vcc, exec, s[0:1]
	s_cbranch_vccnz .LBB0_577
	s_barrier
	s_branch .LBB0_577

.LBB0_659:
	v_mbcnt_lo_u32_b32 v250, -1, 0
	v_mbcnt_hi_u32_b32 v250, -1, v250
	v_and_b32_e32 v250, 16, v250
	v_mul_u32_u24_e32 v250, 3, v250
	v_lshrrev_b32_e32 v250, 1, v250
	v_mov_b32_e32 v251, 0
	v_lshl_add_u32 v144, s45, 8, v146
	v_lshl_or_b32 v142, s46, 8, v148
	v_ashrrev_i32_e32 v145, 31, v144
	v_ashrrev_i32_e32 v143, 31, v142
	v_lshlrev_b64 v[140:141], 10, v[144:145]
	v_lshl_add_u64 v[140:141], v[140:141], 0, v[142:143]
	v_lshlrev_b64 v[140:141], 1, v[140:141]
	v_lshl_add_u64 v[152:153], s[64:65], 0, v[140:141]
	global_load_dwordx2 v[154:155], v[152:153], off
	global_load_dwordx2 v[156:157], v[152:153], off offset:32
	global_load_dwordx2 v[158:159], v[152:153], off offset:256
	s_nop 0
	global_load_dwordx2 v[152:153], v[152:153], off offset:288
	v_or_b32_e32 v160, 16, v144
	v_ashrrev_i32_e32 v161, 31, v160
	v_lshlrev_b64 v[160:161], 10, v[160:161]
	v_lshl_add_u64 v[160:161], v[160:161], 0, v[142:143]
	v_lshl_add_u64 v[162:163], s[62:63], 0, v[140:141]
	v_lshlrev_b64 v[160:161], 1, v[160:161]
	v_lshl_add_u64 v[164:165], s[64:65], 0, v[160:161]
	s_and_b64 vcc, exec, s[2:3]
	s_mov_b64 s[2:3], -1
	s_waitcnt vmcnt(0)
	v_lshlrev_b32_e32 v166, 16, v154
	v_and_b32_e32 v167, 0xffff0000, v154
	v_lshlrev_b32_e32 v154, 16, v155
	v_and_b32_e32 v155, 0xffff0000, v155
	v_lshlrev_b32_e32 v168, 16, v156
	v_and_b32_e32 v169, 0xffff0000, v156
	v_lshlrev_b32_e32 v156, 16, v157
	v_and_b32_e32 v157, 0xffff0000, v157
	v_lshlrev_b32_e32 v170, 16, v158
	v_and_b32_e32 v171, 0xffff0000, v158
	v_lshlrev_b32_e32 v158, 16, v159
	v_and_b32_e32 v159, 0xffff0000, v159
	v_lshlrev_b32_e32 v172, 16, v152
	v_and_b32_e32 v173, 0xffff0000, v152
	v_lshlrev_b32_e32 v152, 16, v153
	v_and_b32_e32 v153, 0xffff0000, v153
	v_pk_fma_f32 v[126:127], v[154:155], s[10:11], v[126:127] op_sel_hi:[1,0,1]
	v_pk_fma_f32 v[124:125], v[166:167], s[10:11], v[124:125] op_sel_hi:[1,0,1]
	v_pk_fma_f32 v[122:123], v[156:157], s[10:11], v[122:123] op_sel_hi:[1,0,1]
	v_pk_fma_f32 v[120:121], v[168:169], s[10:11], v[120:121] op_sel_hi:[1,0,1]
	v_pk_fma_f32 v[118:119], v[158:159], s[10:11], v[118:119] op_sel_hi:[1,0,1]
	v_pk_fma_f32 v[116:117], v[170:171], s[10:11], v[116:117] op_sel_hi:[1,0,1]
	v_pk_fma_f32 v[114:115], v[152:153], s[10:11], v[114:115] op_sel_hi:[1,0,1]
	v_pk_fma_f32 v[112:113], v[172:173], s[10:11], v[112:113] op_sel_hi:[1,0,1]
	v_cvt_pk_bf16_f32 v124, v124, v125
	v_cvt_pk_bf16_f32 v125, v126, v127
	v_cvt_pk_bf16_f32 v126, v120, v121
	v_cvt_pk_bf16_f32 v127, v122, v123
	v_cvt_pk_bf16_f32 v116, v116, v117
	v_cvt_pk_bf16_f32 v117, v118, v119
	v_cvt_pk_bf16_f32 v118, v112, v113
	v_cvt_pk_bf16_f32 v119, v114, v115
	v_lshl_add_u64 v[162:163], v[162:163], 0, v[250:251]
	s_nop 0
	v_permlane16_swap_b32 v124, v126
	v_permlane16_swap_b32 v125, v127
	v_permlane16_swap_b32 v116, v118
	v_permlane16_swap_b32 v117, v119
	global_store_dwordx4 v[162:163], v[124:127], off
	global_store_dwordx4 v[162:163], v[116:119], off offset:256
	s_nop 0
	v_lshl_add_u64 v[248:249], v[164:165], 0, v[250:251]
	global_load_dwordx4 v[112:115], v[248:249], off
	s_nop 0
	global_load_dwordx4 v[116:119], v[248:249], off offset:256
	v_or_b32_e32 v120, 32, v144
	v_ashrrev_i32_e32 v121, 31, v120
	v_lshlrev_b64 v[120:121], 10, v[120:121]
	v_lshl_add_u64 v[120:121], v[120:121], 0, v[142:143]
	v_lshlrev_b64 v[120:121], 1, v[120:121]
	v_lshl_add_u64 v[122:123], s[62:63], 0, v[160:161]
	v_lshl_add_u64 v[124:125], s[64:65], 0, v[120:121]
	s_waitcnt vmcnt(1)
	v_permlane16_swap_b32 v112, v114
	v_permlane16_swap_b32 v113, v115
	s_nop 0
	v_lshlrev_b32_e32 v126, 16, v112
	v_and_b32_e32 v127, 0xffff0000, v112
	v_lshlrev_b32_e32 v112, 16, v113
	v_and_b32_e32 v113, 0xffff0000, v113
	v_lshlrev_b32_e32 v152, 16, v114
	v_and_b32_e32 v153, 0xffff0000, v114
	v_lshlrev_b32_e32 v114, 16, v115
	v_and_b32_e32 v115, 0xffff0000, v115
	s_waitcnt vmcnt(0)
	v_permlane16_swap_b32 v116, v118
	v_permlane16_swap_b32 v117, v119
	s_nop 0
	v_lshlrev_b32_e32 v154, 16, v116
	v_and_b32_e32 v155, 0xffff0000, v116
	v_lshlrev_b32_e32 v116, 16, v117
	v_and_b32_e32 v117, 0xffff0000, v117
	v_lshlrev_b32_e32 v156, 16, v118
	v_and_b32_e32 v157, 0xffff0000, v118
	v_lshlrev_b32_e32 v118, 16, v119
	v_and_b32_e32 v119, 0xffff0000, v119
	v_pk_fma_f32 v[110:111], v[112:113], s[10:11], v[110:111] op_sel_hi:[1,0,1]
	v_pk_fma_f32 v[108:109], v[126:127], s[10:11], v[108:109] op_sel_hi:[1,0,1]
	v_pk_fma_f32 v[106:107], v[114:115], s[10:11], v[106:107] op_sel_hi:[1,0,1]
	v_pk_fma_f32 v[104:105], v[152:153], s[10:11], v[104:105] op_sel_hi:[1,0,1]
	v_pk_fma_f32 v[102:103], v[116:117], s[10:11], v[102:103] op_sel_hi:[1,0,1]
	v_pk_fma_f32 v[100:101], v[154:155], s[10:11], v[100:101] op_sel_hi:[1,0,1]
	v_pk_fma_f32 v[98:99], v[118:119], s[10:11], v[98:99] op_sel_hi:[1,0,1]
	v_pk_fma_f32 v[96:97], v[156:157], s[10:11], v[96:97] op_sel_hi:[1,0,1]
	v_cvt_pk_bf16_f32 v108, v108, v109
	v_cvt_pk_bf16_f32 v109, v110, v111
	v_cvt_pk_bf16_f32 v110, v104, v105
	v_cvt_pk_bf16_f32 v111, v106, v107
	v_cvt_pk_bf16_f32 v100, v100, v101
	v_cvt_pk_bf16_f32 v101, v102, v103
	v_cvt_pk_bf16_f32 v102, v96, v97
	v_cvt_pk_bf16_f32 v103, v98, v99
	v_lshl_add_u64 v[122:123], v[122:123], 0, v[250:251]
	s_nop 0
	v_permlane16_swap_b32 v108, v110
	v_permlane16_swap_b32 v109, v111
	v_permlane16_swap_b32 v100, v102
	v_permlane16_swap_b32 v101, v103
	global_store_dwordx4 v[122:123], v[108:111], off
	global_store_dwordx4 v[122:123], v[100:103], off offset:256
	s_nop 0
	v_lshl_add_u64 v[248:249], v[124:125], 0, v[250:251]
	global_load_dwordx4 v[96:99], v[248:249], off
	s_nop 0
	global_load_dwordx4 v[100:103], v[248:249], off offset:256
	v_or_b32_e32 v104, 48, v144
	v_ashrrev_i32_e32 v105, 31, v104
	v_lshlrev_b64 v[104:105], 10, v[104:105]
	v_lshl_add_u64 v[104:105], v[104:105], 0, v[142:143]
	v_lshlrev_b64 v[104:105], 1, v[104:105]
	v_lshl_add_u64 v[106:107], s[62:63], 0, v[120:121]
	v_lshl_add_u64 v[108:109], s[64:65], 0, v[104:105]
	s_waitcnt vmcnt(1)
	v_permlane16_swap_b32 v96, v98
	v_permlane16_swap_b32 v97, v99
	s_nop 0
	v_lshlrev_b32_e32 v110, 16, v96
	v_and_b32_e32 v111, 0xffff0000, v96
	v_lshlrev_b32_e32 v96, 16, v97
	v_and_b32_e32 v97, 0xffff0000, v97
	v_lshlrev_b32_e32 v112, 16, v98
	v_and_b32_e32 v113, 0xffff0000, v98
	v_lshlrev_b32_e32 v98, 16, v99
	v_and_b32_e32 v99, 0xffff0000, v99
	s_waitcnt vmcnt(0)
	v_permlane16_swap_b32 v100, v102
	v_permlane16_swap_b32 v101, v103
	s_nop 0
	v_lshlrev_b32_e32 v114, 16, v100
	v_and_b32_e32 v115, 0xffff0000, v100
	v_lshlrev_b32_e32 v100, 16, v101
	v_and_b32_e32 v101, 0xffff0000, v101
	v_lshlrev_b32_e32 v116, 16, v102
	v_and_b32_e32 v117, 0xffff0000, v102
	v_lshlrev_b32_e32 v102, 16, v103
	v_and_b32_e32 v103, 0xffff0000, v103
	v_pk_fma_f32 v[94:95], v[96:97], s[10:11], v[94:95] op_sel_hi:[1,0,1]
	v_pk_fma_f32 v[92:93], v[110:111], s[10:11], v[92:93] op_sel_hi:[1,0,1]
	v_pk_fma_f32 v[90:91], v[98:99], s[10:11], v[90:91] op_sel_hi:[1,0,1]
	v_pk_fma_f32 v[88:89], v[112:113], s[10:11], v[88:89] op_sel_hi:[1,0,1]
	v_pk_fma_f32 v[86:87], v[100:101], s[10:11], v[86:87] op_sel_hi:[1,0,1]
	v_pk_fma_f32 v[84:85], v[114:115], s[10:11], v[84:85] op_sel_hi:[1,0,1]
	v_pk_fma_f32 v[82:83], v[102:103], s[10:11], v[82:83] op_sel_hi:[1,0,1]
	v_pk_fma_f32 v[80:81], v[116:117], s[10:11], v[80:81] op_sel_hi:[1,0,1]
	v_cvt_pk_bf16_f32 v92, v92, v93
	v_cvt_pk_bf16_f32 v93, v94, v95
	v_cvt_pk_bf16_f32 v94, v88, v89
	v_cvt_pk_bf16_f32 v95, v90, v91
	v_cvt_pk_bf16_f32 v84, v84, v85
	v_cvt_pk_bf16_f32 v85, v86, v87
	v_cvt_pk_bf16_f32 v86, v80, v81
	v_cvt_pk_bf16_f32 v87, v82, v83
	v_lshl_add_u64 v[106:107], v[106:107], 0, v[250:251]
	s_nop 0
	v_permlane16_swap_b32 v92, v94
	v_permlane16_swap_b32 v93, v95
	v_permlane16_swap_b32 v84, v86
	v_permlane16_swap_b32 v85, v87
	global_store_dwordx4 v[106:107], v[92:95], off
	global_store_dwordx4 v[106:107], v[84:87], off offset:256
	s_nop 0
	v_lshl_add_u64 v[248:249], v[108:109], 0, v[250:251]
	global_load_dwordx4 v[80:83], v[248:249], off
	s_nop 0
	global_load_dwordx4 v[84:87], v[248:249], off offset:256
	v_lshl_add_u64 v[88:89], v[140:141], 0, s[12:13]
	v_lshl_add_u64 v[90:91], s[62:63], 0, v[104:105]
	v_lshl_add_u64 v[92:93], s[64:65], 0, v[88:89]
	s_waitcnt vmcnt(1)
	v_permlane16_swap_b32 v80, v82
	v_permlane16_swap_b32 v81, v83
	s_nop 0
	v_lshlrev_b32_e32 v94, 16, v80
	v_and_b32_e32 v95, 0xffff0000, v80
	v_lshlrev_b32_e32 v80, 16, v81
	v_and_b32_e32 v81, 0xffff0000, v81
	v_lshlrev_b32_e32 v96, 16, v82
	v_and_b32_e32 v97, 0xffff0000, v82
	v_lshlrev_b32_e32 v82, 16, v83
	v_and_b32_e32 v83, 0xffff0000, v83
	s_waitcnt vmcnt(0)
	v_permlane16_swap_b32 v84, v86
	v_permlane16_swap_b32 v85, v87
	s_nop 0
	v_lshlrev_b32_e32 v98, 16, v84
	v_and_b32_e32 v99, 0xffff0000, v84
	v_lshlrev_b32_e32 v84, 16, v85
	v_and_b32_e32 v85, 0xffff0000, v85
	v_lshlrev_b32_e32 v100, 16, v86
	v_and_b32_e32 v101, 0xffff0000, v86
	v_lshlrev_b32_e32 v86, 16, v87
	v_and_b32_e32 v87, 0xffff0000, v87
	v_pk_fma_f32 v[78:79], v[80:81], s[10:11], v[78:79] op_sel_hi:[1,0,1]
	v_pk_fma_f32 v[76:77], v[94:95], s[10:11], v[76:77] op_sel_hi:[1,0,1]
	v_pk_fma_f32 v[74:75], v[82:83], s[10:11], v[74:75] op_sel_hi:[1,0,1]
	v_pk_fma_f32 v[72:73], v[96:97], s[10:11], v[72:73] op_sel_hi:[1,0,1]
	v_pk_fma_f32 v[70:71], v[84:85], s[10:11], v[70:71] op_sel_hi:[1,0,1]
	v_pk_fma_f32 v[68:69], v[98:99], s[10:11], v[68:69] op_sel_hi:[1,0,1]
	v_pk_fma_f32 v[66:67], v[86:87], s[10:11], v[66:67] op_sel_hi:[1,0,1]
	v_pk_fma_f32 v[64:65], v[100:101], s[10:11], v[64:65] op_sel_hi:[1,0,1]
	v_cvt_pk_bf16_f32 v76, v76, v77
	v_cvt_pk_bf16_f32 v77, v78, v79
	v_cvt_pk_bf16_f32 v78, v72, v73
	v_cvt_pk_bf16_f32 v79, v74, v75
	v_cvt_pk_bf16_f32 v68, v68, v69
	v_cvt_pk_bf16_f32 v69, v70, v71
	v_cvt_pk_bf16_f32 v70, v64, v65
	v_cvt_pk_bf16_f32 v71, v66, v67
	v_lshl_add_u64 v[90:91], v[90:91], 0, v[250:251]
	s_nop 0
	v_permlane16_swap_b32 v76, v78
	v_permlane16_swap_b32 v77, v79
	v_permlane16_swap_b32 v68, v70
	v_permlane16_swap_b32 v69, v71
	global_store_dwordx4 v[90:91], v[76:79], off
	global_store_dwordx4 v[90:91], v[68:71], off offset:256
	s_nop 0
	v_lshl_add_u64 v[248:249], v[92:93], 0, v[250:251]
	global_load_dwordx4 v[64:67], v[248:249], off
	s_nop 0
	global_load_dwordx4 v[68:71], v[248:249], off offset:256
	v_lshl_add_u64 v[72:73], v[140:141], 0, s[14:15]
	v_lshl_add_u64 v[74:75], s[62:63], 0, v[88:89]
	v_lshl_add_u64 v[76:77], s[64:65], 0, v[72:73]
	s_waitcnt vmcnt(1)
	v_permlane16_swap_b32 v64, v66
	v_permlane16_swap_b32 v65, v67
	s_nop 0
	v_lshlrev_b32_e32 v78, 16, v64
	v_and_b32_e32 v79, 0xffff0000, v64
	v_lshlrev_b32_e32 v64, 16, v65
	v_and_b32_e32 v65, 0xffff0000, v65
	v_lshlrev_b32_e32 v80, 16, v66
	v_and_b32_e32 v81, 0xffff0000, v66
	v_lshlrev_b32_e32 v66, 16, v67
	v_and_b32_e32 v67, 0xffff0000, v67
	s_waitcnt vmcnt(0)
	v_permlane16_swap_b32 v68, v70
	v_permlane16_swap_b32 v69, v71
	s_nop 0
	v_lshlrev_b32_e32 v82, 16, v68
	v_and_b32_e32 v83, 0xffff0000, v68
	v_lshlrev_b32_e32 v68, 16, v69
	v_and_b32_e32 v69, 0xffff0000, v69
	v_lshlrev_b32_e32 v84, 16, v70
	v_and_b32_e32 v85, 0xffff0000, v70
	v_lshlrev_b32_e32 v70, 16, v71
	v_and_b32_e32 v71, 0xffff0000, v71
	v_pk_fma_f32 v[62:63], v[64:65], s[10:11], v[62:63] op_sel_hi:[1,0,1]
	v_pk_fma_f32 v[60:61], v[78:79], s[10:11], v[60:61] op_sel_hi:[1,0,1]
	v_pk_fma_f32 v[58:59], v[66:67], s[10:11], v[58:59] op_sel_hi:[1,0,1]
	v_pk_fma_f32 v[56:57], v[80:81], s[10:11], v[56:57] op_sel_hi:[1,0,1]
	v_pk_fma_f32 v[54:55], v[68:69], s[10:11], v[54:55] op_sel_hi:[1,0,1]
	v_pk_fma_f32 v[52:53], v[82:83], s[10:11], v[52:53] op_sel_hi:[1,0,1]
	v_pk_fma_f32 v[50:51], v[70:71], s[10:11], v[50:51] op_sel_hi:[1,0,1]
	v_pk_fma_f32 v[48:49], v[84:85], s[10:11], v[48:49] op_sel_hi:[1,0,1]
	v_cvt_pk_bf16_f32 v60, v60, v61
	v_cvt_pk_bf16_f32 v61, v62, v63
	v_cvt_pk_bf16_f32 v62, v56, v57
	v_cvt_pk_bf16_f32 v63, v58, v59
	v_cvt_pk_bf16_f32 v52, v52, v53
	v_cvt_pk_bf16_f32 v53, v54, v55
	v_cvt_pk_bf16_f32 v54, v48, v49
	v_cvt_pk_bf16_f32 v55, v50, v51
	v_lshl_add_u64 v[74:75], v[74:75], 0, v[250:251]
	s_nop 0
	v_permlane16_swap_b32 v60, v62
	v_permlane16_swap_b32 v61, v63
	v_permlane16_swap_b32 v52, v54
	v_permlane16_swap_b32 v53, v55
	global_store_dwordx4 v[74:75], v[60:63], off
	global_store_dwordx4 v[74:75], v[52:55], off offset:256
	s_nop 0
	v_lshl_add_u64 v[248:249], v[76:77], 0, v[250:251]
	global_load_dwordx4 v[48:51], v[248:249], off
	s_nop 0
	global_load_dwordx4 v[52:55], v[248:249], off offset:256
	v_lshl_add_u64 v[56:57], v[140:141], 0, s[16:17]
	v_lshl_add_u64 v[58:59], s[62:63], 0, v[72:73]
	v_lshl_add_u64 v[60:61], s[64:65], 0, v[56:57]
	s_waitcnt vmcnt(1)
	v_permlane16_swap_b32 v48, v50
	v_permlane16_swap_b32 v49, v51
	s_nop 0
	v_lshlrev_b32_e32 v62, 16, v48
	v_and_b32_e32 v63, 0xffff0000, v48
	v_lshlrev_b32_e32 v48, 16, v49
	v_and_b32_e32 v49, 0xffff0000, v49
	v_lshlrev_b32_e32 v64, 16, v50
	v_and_b32_e32 v65, 0xffff0000, v50
	v_lshlrev_b32_e32 v50, 16, v51
	v_and_b32_e32 v51, 0xffff0000, v51
	s_waitcnt vmcnt(0)
	v_permlane16_swap_b32 v52, v54
	v_permlane16_swap_b32 v53, v55
	s_nop 0
	v_lshlrev_b32_e32 v66, 16, v52
	v_and_b32_e32 v67, 0xffff0000, v52
	v_lshlrev_b32_e32 v52, 16, v53
	v_and_b32_e32 v53, 0xffff0000, v53
	v_lshlrev_b32_e32 v68, 16, v54
	v_and_b32_e32 v69, 0xffff0000, v54
	v_lshlrev_b32_e32 v54, 16, v55
	v_and_b32_e32 v55, 0xffff0000, v55
	v_pk_fma_f32 v[46:47], v[48:49], s[10:11], v[46:47] op_sel_hi:[1,0,1]
	v_pk_fma_f32 v[44:45], v[62:63], s[10:11], v[44:45] op_sel_hi:[1,0,1]
	v_pk_fma_f32 v[42:43], v[50:51], s[10:11], v[42:43] op_sel_hi:[1,0,1]
	v_pk_fma_f32 v[40:41], v[64:65], s[10:11], v[40:41] op_sel_hi:[1,0,1]
	v_pk_fma_f32 v[38:39], v[52:53], s[10:11], v[38:39] op_sel_hi:[1,0,1]
	v_pk_fma_f32 v[36:37], v[66:67], s[10:11], v[36:37] op_sel_hi:[1,0,1]
	v_pk_fma_f32 v[34:35], v[54:55], s[10:11], v[34:35] op_sel_hi:[1,0,1]
	v_pk_fma_f32 v[32:33], v[68:69], s[10:11], v[32:33] op_sel_hi:[1,0,1]
	v_cvt_pk_bf16_f32 v44, v44, v45
	v_cvt_pk_bf16_f32 v45, v46, v47
	v_cvt_pk_bf16_f32 v46, v40, v41
	v_cvt_pk_bf16_f32 v47, v42, v43
	v_cvt_pk_bf16_f32 v36, v36, v37
	v_cvt_pk_bf16_f32 v37, v38, v39
	v_cvt_pk_bf16_f32 v38, v32, v33
	v_cvt_pk_bf16_f32 v39, v34, v35
	v_lshl_add_u64 v[58:59], v[58:59], 0, v[250:251]
	s_nop 0
	v_permlane16_swap_b32 v44, v46
	v_permlane16_swap_b32 v45, v47
	v_permlane16_swap_b32 v36, v38
	v_permlane16_swap_b32 v37, v39
	global_store_dwordx4 v[58:59], v[44:47], off
	global_store_dwordx4 v[58:59], v[36:39], off offset:256
	s_nop 0
	v_lshl_add_u64 v[248:249], v[60:61], 0, v[250:251]
	global_load_dwordx4 v[32:35], v[248:249], off
	s_nop 0
	global_load_dwordx4 v[36:39], v[248:249], off offset:256
	v_lshl_add_u64 v[40:41], v[140:141], 0, s[18:19]
	v_lshl_add_u64 v[42:43], s[62:63], 0, v[56:57]
	v_lshl_add_u64 v[44:45], s[64:65], 0, v[40:41]
	s_waitcnt vmcnt(1)
	v_permlane16_swap_b32 v32, v34
	v_permlane16_swap_b32 v33, v35
	s_nop 0
	v_lshlrev_b32_e32 v46, 16, v32
	v_and_b32_e32 v47, 0xffff0000, v32
	v_lshlrev_b32_e32 v32, 16, v33
	v_and_b32_e32 v33, 0xffff0000, v33
	v_lshlrev_b32_e32 v48, 16, v34
	v_and_b32_e32 v49, 0xffff0000, v34
	v_lshlrev_b32_e32 v34, 16, v35
	v_and_b32_e32 v35, 0xffff0000, v35
	s_waitcnt vmcnt(0)
	v_permlane16_swap_b32 v36, v38
	v_permlane16_swap_b32 v37, v39
	s_nop 0
	v_lshlrev_b32_e32 v50, 16, v36
	v_and_b32_e32 v51, 0xffff0000, v36
	v_lshlrev_b32_e32 v36, 16, v37
	v_and_b32_e32 v37, 0xffff0000, v37
	v_lshlrev_b32_e32 v52, 16, v38
	v_and_b32_e32 v53, 0xffff0000, v38
	v_lshlrev_b32_e32 v38, 16, v39
	v_and_b32_e32 v39, 0xffff0000, v39
	v_pk_fma_f32 v[30:31], v[32:33], s[10:11], v[30:31] op_sel_hi:[1,0,1]
	v_pk_fma_f32 v[28:29], v[46:47], s[10:11], v[28:29] op_sel_hi:[1,0,1]
	v_pk_fma_f32 v[26:27], v[34:35], s[10:11], v[26:27] op_sel_hi:[1,0,1]
	v_pk_fma_f32 v[24:25], v[48:49], s[10:11], v[24:25] op_sel_hi:[1,0,1]
	v_pk_fma_f32 v[22:23], v[36:37], s[10:11], v[22:23] op_sel_hi:[1,0,1]
	v_pk_fma_f32 v[20:21], v[50:51], s[10:11], v[20:21] op_sel_hi:[1,0,1]
	v_pk_fma_f32 v[18:19], v[38:39], s[10:11], v[18:19] op_sel_hi:[1,0,1]
	v_pk_fma_f32 v[16:17], v[52:53], s[10:11], v[16:17] op_sel_hi:[1,0,1]
	v_cvt_pk_bf16_f32 v28, v28, v29
	v_cvt_pk_bf16_f32 v29, v30, v31
	v_cvt_pk_bf16_f32 v30, v24, v25
	v_cvt_pk_bf16_f32 v31, v26, v27
	v_cvt_pk_bf16_f32 v20, v20, v21
	v_cvt_pk_bf16_f32 v21, v22, v23
	v_cvt_pk_bf16_f32 v22, v16, v17
	v_cvt_pk_bf16_f32 v23, v18, v19
	v_lshl_add_u64 v[42:43], v[42:43], 0, v[250:251]
	s_nop 0
	v_permlane16_swap_b32 v28, v30
	v_permlane16_swap_b32 v29, v31
	v_permlane16_swap_b32 v20, v22
	v_permlane16_swap_b32 v21, v23
	global_store_dwordx4 v[42:43], v[28:31], off
	global_store_dwordx4 v[42:43], v[20:23], off offset:256
	s_nop 0
	v_lshl_add_u64 v[248:249], v[44:45], 0, v[250:251]
	global_load_dwordx4 v[16:19], v[248:249], off
	s_nop 0
	global_load_dwordx4 v[20:23], v[248:249], off offset:256
	v_lshl_add_u64 v[24:25], s[62:63], 0, v[40:41]
	s_waitcnt vmcnt(1)
	v_permlane16_swap_b32 v16, v18
	v_permlane16_swap_b32 v17, v19
	s_nop 0
	v_lshlrev_b32_e32 v26, 16, v16
	v_and_b32_e32 v27, 0xffff0000, v16
	v_lshlrev_b32_e32 v16, 16, v17
	v_and_b32_e32 v17, 0xffff0000, v17
	v_lshlrev_b32_e32 v28, 16, v18
	v_and_b32_e32 v29, 0xffff0000, v18
	v_lshlrev_b32_e32 v18, 16, v19
	v_and_b32_e32 v19, 0xffff0000, v19
	s_waitcnt vmcnt(0)
	v_permlane16_swap_b32 v20, v22
	v_permlane16_swap_b32 v21, v23
	s_nop 0
	v_lshlrev_b32_e32 v30, 16, v20
	v_and_b32_e32 v31, 0xffff0000, v20
	v_lshlrev_b32_e32 v20, 16, v21
	v_and_b32_e32 v21, 0xffff0000, v21
	v_lshlrev_b32_e32 v32, 16, v22
	v_and_b32_e32 v33, 0xffff0000, v22
	v_lshlrev_b32_e32 v22, 16, v23
	v_and_b32_e32 v23, 0xffff0000, v23
	v_pk_fma_f32 v[14:15], v[16:17], s[10:11], v[14:15] op_sel_hi:[1,0,1]
	v_pk_fma_f32 v[12:13], v[26:27], s[10:11], v[12:13] op_sel_hi:[1,0,1]
	v_pk_fma_f32 v[10:11], v[18:19], s[10:11], v[10:11] op_sel_hi:[1,0,1]
	v_pk_fma_f32 v[8:9], v[28:29], s[10:11], v[8:9] op_sel_hi:[1,0,1]
	v_pk_fma_f32 v[6:7], v[20:21], s[10:11], v[6:7] op_sel_hi:[1,0,1]
	v_pk_fma_f32 v[4:5], v[30:31], s[10:11], v[4:5] op_sel_hi:[1,0,1]
	v_pk_fma_f32 v[2:3], v[22:23], s[10:11], v[2:3] op_sel_hi:[1,0,1]
	v_pk_fma_f32 v[0:1], v[32:33], s[10:11], v[0:1] op_sel_hi:[1,0,1]
	v_cvt_pk_bf16_f32 v12, v12, v13
	v_cvt_pk_bf16_f32 v13, v14, v15
	v_cvt_pk_bf16_f32 v14, v8, v9
	v_cvt_pk_bf16_f32 v15, v10, v11
	v_cvt_pk_bf16_f32 v4, v4, v5
	v_cvt_pk_bf16_f32 v5, v6, v7
	v_cvt_pk_bf16_f32 v6, v0, v1
	v_cvt_pk_bf16_f32 v7, v2, v3
	v_lshl_add_u64 v[24:25], v[24:25], 0, v[250:251]
	s_nop 0
	v_permlane16_swap_b32 v12, v14
	v_permlane16_swap_b32 v13, v15
	v_permlane16_swap_b32 v4, v6
	v_permlane16_swap_b32 v5, v7
	global_store_dwordx4 v[24:25], v[12:15], off
	global_store_dwordx4 v[24:25], v[4:7], off offset:256
	s_nop 0
	s_cbranch_vccnz .LBB0_644
	s_andn2_b64 vcc, exec, s[0:1]
	s_cbranch_vccnz .LBB0_643
	s_barrier
	s_branch .LBB0_643
